# saddr3-all-loops
# speedup vs baseline: 1.0266x; 1.0004x over previous
; #define PG8_STAGE(bufoff, gbase, voff) do { _Pragma("unroll") for (int _i = 0; _i < 2; ++_i) \
;         __builtin_amdgcn_global_load_lds((const unsigned*)((const char*)(gbase) + (voff)[_i]), (LAS unsigned*)(lds + (bufoff) + ldsw + _i * 8192), 16, 0, 0); } while (0)
; #define PG8_LDA(dst, b, h) do { _Pragma("unroll") for (int m = 0; m < 4; ++m) _Pragma("unroll") for (int k = 0; k < 2; ++k) dst[m][k] = *(const LAS bf16x8*)(lds + PG8_SA(b, h) + aoff + m * 2048 + k * 1024); } while (0)
; #define PG8_LDB(dst, b, h) do { _Pragma("unroll") for (int n = 0; n < 2; ++n) _Pragma("unroll") for (int k = 0; k < 2; ++k) dst[n][k] = *(const LAS bf16x8*)(lds + PG8_SB(b, h) + boff + n * 2048 + k * 1024); } while (0)
; #define PG8_MMA(ai, bj, At, Bt) do { __builtin_amdgcn_s_setprio(1); _Pragma("unroll") for (int m = 0; m < 4; ++m) _Pragma("unroll") for (int n = 0; n < 2; ++n) _Pragma("unroll") for (int k = 0; k < 2; ++k) \
;         acc[ai][bj][m][n] = __builtin_amdgcn_mfma_f32_16x16x32_bf16(Bt[n][k], At[m][k], acc[ai][bj][m][n], 0, 0, 0); __builtin_amdgcn_s_setprio(0); } while (0)
; #define PG8_WAIT_V(n) asm volatile("s_waitcnt vmcnt(" #n ")" ::: "memory")
; #define PG8_WAIT_L(n) asm volatile("s_waitcnt lgkmcnt(" #n ")" ::: "memory")
; template <class Epi, class Sched, bool ATILE = false>
; __device__ __forceinline__ void gemm_phase(LAS unsigned char* lds, const Gemm g, const Sched& S, const Epi& E) {
;     ...
;         for (int t = 0; t < nt; t += 2) {
;             const bool last = (t == nt - 2);
;             const char* a1 = cA + (size_t)(t + 1) * kstepA;
;             const char* a2 = last ? nA : cA + (size_t)(t + 2) * kstepA; const char* b2 = last ? nB : cB + (size_t)(t + 2) * kstep;
;             const char* a3 = a2 + kstepA; const char* b3 = b2 + kstep;
;             PG8_LDB(B0, 0, 0); PG8_SCHED; PG8_LDA(At, 0, 0); PG8_STAGE(PG8_SA(1, 1), a1 + hstepA, voffA);
;             PG8_WAIT_L(8); PG8_BAR; PG8_WAIT_L(0); PG8_MMA(0, 0, At, B0); PG8_BAR; PG8_SCHED;
;             PG8_LDB(B1, 0, 1); PG8_STAGE(PG8_SB(0, 0), b2, voffB);
;             PG8_BAR; PG8_WAIT_L(0); PG8_MMA(0, 1, At, B1); PG8_BAR;
;             PG8_LDA(At, 0, 1); PG8_STAGE(PG8_SA(0, 0), a2, voffA);
;             PG8_BAR; PG8_WAIT_L(0); PG8_MMA(1, 0, At, B0); PG8_BAR; PG8_SCHED;
;             PG8_STAGE(PG8_SB(0, 1), b2 + hstepB, voffB);
;             PG8_WAIT_V(6); PG8_BAR; PG8_MMA(1, 1, At, B1); PG8_BAR;
.LBB0_739:
	ds_read_b128 v[20:23], v165
	ds_read_b128 v[28:31], v165 offset:1024
	ds_read_b128 v[136:139], v165 offset:2048
	ds_read_b128 v[140:143], v165 offset:3072
	s_add_i32 s62, s26, 2
	s_add_u32 s27, s24, 0x4000
	s_addc_u32 s28, s25, 0
	s_cmp_eq_u32 s11, s26
	s_cselect_b32 s30, s20, s27
	s_cselect_b32 s31, s21, s28
	s_cselect_b32 s26, s22, s60
	s_cselect_b32 s27, s23, s61
	s_add_u32 s28, s30, 0x8000
	s_addc_u32 s29, s31, 0
	s_add_i32 m0, s34, 0xc000
	ds_read_b128 v[144:147], v167
	ds_read_b128 v[148:151], v167 offset:1024
	ds_read_b128 v[200:203], v167 offset:2048
	ds_read_b128 v[204:207], v167 offset:3072
	ds_read_b128 v[208:211], v167 offset:4096
	ds_read_b128 v[212:215], v167 offset:5120
	ds_read_b128 v[220:223], v167 offset:6144
	ds_read_b128 v[224:227], v167 offset:7168
	global_load_lds_dwordx4 v194, s[24:25]
	s_add_i32 m0, s34, 0xe000
	s_nop 0
	global_load_lds_dwordx4 v196, s[24:25]
	s_waitcnt lgkmcnt(8)
	s_barrier
	s_waitcnt lgkmcnt(0)
	s_setprio 1
	s_waitcnt lgkmcnt(0)
	v_mfma_f32_16x16x32_bf16 v[0:3], v[20:23], v[144:147], v[0:3]
	v_mfma_f32_16x16x32_bf16 v[4:7], v[136:139], v[144:147], v[4:7]
	v_mfma_f32_16x16x32_bf16 v[44:47], v[20:23], v[200:203], v[44:47]
	v_mfma_f32_16x16x32_bf16 v[36:39], v[136:139], v[200:203], v[36:39]
	v_mfma_f32_16x16x32_bf16 v[52:55], v[20:23], v[208:211], v[52:55]
	v_mfma_f32_16x16x32_bf16 v[48:51], v[136:139], v[208:211], v[48:51]
	v_mfma_f32_16x16x32_bf16 v[92:95], v[20:23], v[220:223], v[92:95]
	v_mfma_f32_16x16x32_bf16 v[84:87], v[136:139], v[220:223], v[84:87]
	v_mfma_f32_16x16x32_bf16 v[0:3], v[28:31], v[148:151], v[0:3]
	v_mfma_f32_16x16x32_bf16 v[4:7], v[140:143], v[148:151], v[4:7]
	v_mfma_f32_16x16x32_bf16 v[44:47], v[28:31], v[204:207], v[44:47]
	v_mfma_f32_16x16x32_bf16 v[36:39], v[140:143], v[204:207], v[36:39]
	v_mfma_f32_16x16x32_bf16 v[52:55], v[28:31], v[212:215], v[52:55]
	v_mfma_f32_16x16x32_bf16 v[48:51], v[140:143], v[212:215], v[48:51]
	v_mfma_f32_16x16x32_bf16 v[92:95], v[28:31], v[224:227], v[92:95]
	v_mfma_f32_16x16x32_bf16 v[84:87], v[140:143], v[224:227], v[84:87]
	s_setprio 0
	s_barrier
	s_add_i32 s63, s52, s33
	s_add_u32 s98, s26, s6
	s_addc_u32 s99, s27, s7
	s_mov_b32 m0, s63
	ds_read_b128 v[228:231], v177
	ds_read_b128 v[232:235], v177 offset:1024
	ds_read_b128 v[236:239], v177 offset:2048
	ds_read_b128 v[240:243], v177 offset:3072
	global_load_lds_dwordx4 v170, s[26:27]
	s_add_i32 m0, s63, 0x2000
	s_nop 0
	global_load_lds_dwordx4 v174, s[26:27]
	s_barrier
	s_waitcnt lgkmcnt(0)
	s_setprio 1
	s_waitcnt lgkmcnt(0)
	v_mfma_f32_16x16x32_bf16 v[12:15], v[228:231], v[144:147], v[12:15]
	v_mfma_f32_16x16x32_bf16 v[8:11], v[236:239], v[144:147], v[8:11]
	v_mfma_f32_16x16x32_bf16 v[24:27], v[228:231], v[200:203], v[24:27]
	v_mfma_f32_16x16x32_bf16 v[16:19], v[236:239], v[200:203], v[16:19]
	v_mfma_f32_16x16x32_bf16 v[40:43], v[228:231], v[208:211], v[40:43]
	v_mfma_f32_16x16x32_bf16 v[32:35], v[236:239], v[208:211], v[32:35]
	v_mfma_f32_16x16x32_bf16 v[56:59], v[228:231], v[220:223], v[56:59]
	v_mfma_f32_16x16x32_bf16 v[60:63], v[236:239], v[220:223], v[60:63]
	v_mfma_f32_16x16x32_bf16 v[12:15], v[232:235], v[148:151], v[12:15]
	v_mfma_f32_16x16x32_bf16 v[8:11], v[240:243], v[148:151], v[8:11]
	v_mfma_f32_16x16x32_bf16 v[24:27], v[232:235], v[204:207], v[24:27]
	v_mfma_f32_16x16x32_bf16 v[16:19], v[240:243], v[204:207], v[16:19]
	v_mfma_f32_16x16x32_bf16 v[40:43], v[232:235], v[212:215], v[40:43]
	v_mfma_f32_16x16x32_bf16 v[32:35], v[240:243], v[212:215], v[32:35]
	v_mfma_f32_16x16x32_bf16 v[56:59], v[232:235], v[224:227], v[56:59]
	v_mfma_f32_16x16x32_bf16 v[60:63], v[240:243], v[224:227], v[60:63]
	s_setprio 0
	s_barrier
	s_mov_b32 m0, s34
	ds_read_b128 v[144:147], v167 offset:16384
	ds_read_b128 v[148:151], v167 offset:17408
	ds_read_b128 v[200:203], v167 offset:18432
	ds_read_b128 v[204:207], v167 offset:19456
	ds_read_b128 v[208:211], v167 offset:20480
	ds_read_b128 v[212:215], v167 offset:21504
	ds_read_b128 v[220:223], v167 offset:22528
	ds_read_b128 v[224:227], v167 offset:23552
	global_load_lds_dwordx4 v168, s[30:31]
	s_mov_b32 m0, s35
	s_nop 0
	global_load_lds_dwordx4 v172, s[30:31]
	s_barrier
	s_waitcnt lgkmcnt(0)
	s_setprio 1
	s_waitcnt lgkmcnt(0)
	v_mfma_f32_16x16x32_bf16 v[64:67], v[20:23], v[144:147], v[64:67]
	v_mfma_f32_16x16x32_bf16 v[68:71], v[136:139], v[144:147], v[68:71]
	v_mfma_f32_16x16x32_bf16 v[108:111], v[20:23], v[200:203], v[108:111]
	v_mfma_f32_16x16x32_bf16 v[100:103], v[136:139], v[200:203], v[100:103]
	v_mfma_f32_16x16x32_bf16 v[116:119], v[20:23], v[208:211], v[116:119]
	v_mfma_f32_16x16x32_bf16 v[112:115], v[136:139], v[208:211], v[112:115]
	v_mfma_f32_16x16x32_bf16 v[20:23], v[20:23], v[220:223], v[132:135]
	v_mfma_f32_16x16x32_bf16 v[64:67], v[28:31], v[148:151], v[64:67]
	v_mfma_f32_16x16x32_bf16 v[68:71], v[140:143], v[148:151], v[68:71]
	v_mfma_f32_16x16x32_bf16 v[108:111], v[28:31], v[204:207], v[108:111]
	v_mfma_f32_16x16x32_bf16 v[100:103], v[140:143], v[204:207], v[100:103]
	v_mfma_f32_16x16x32_bf16 v[116:119], v[28:31], v[212:215], v[116:119]
	v_mfma_f32_16x16x32_bf16 v[112:115], v[140:143], v[212:215], v[112:115]
	v_mfma_f32_16x16x32_bf16 v[20:23], v[28:31], v[224:227], v[20:23]
	v_mfma_f32_16x16x32_bf16 v[28:31], v[136:139], v[220:223], v[128:131]
	v_mfma_f32_16x16x32_bf16 v[28:31], v[140:143], v[224:227], v[28:31]
	s_setprio 0
	s_barrier
	s_add_u32 s64, s26, 0x158000
	s_addc_u32 s65, s27, 0
	s_add_i32 s63, s53, s33
	s_mov_b32 m0, s63
	s_nop 0
	global_load_lds_dwordx4 v170, s[64:65]
	s_add_i32 m0, s63, 0x2000
	s_nop 0
	global_load_lds_dwordx4 v174, s[64:65]
	s_waitcnt vmcnt(6)
	s_barrier
; #define PG8_STAGE(bufoff, gbase, voff) do { _Pragma("unroll") for (int _i = 0; _i < 2; ++_i) \
;         __builtin_amdgcn_global_load_lds((const unsigned*)((const char*)(gbase) + (voff)[_i]), (LAS unsigned*)(lds + (bufoff) + ldsw + _i * 8192), 16, 0, 0); } while (0)
; #define PG8_LDA(dst, b, h) do { _Pragma("unroll") for (int m = 0; m < 4; ++m) _Pragma("unroll") for (int k = 0; k < 2; ++k) dst[m][k] = *(const LAS bf16x8*)(lds + PG8_SA(b, h) + aoff + m * 2048 + k * 1024); } while (0)
; #define PG8_LDB(dst, b, h) do { _Pragma("unroll") for (int n = 0; n < 2; ++n) _Pragma("unroll") for (int k = 0; k < 2; ++k) dst[n][k] = *(const LAS bf16x8*)(lds + PG8_SB(b, h) + boff + n * 2048 + k * 1024); } while (0)
; #define PG8_MMA(ai, bj, At, Bt) do { __builtin_amdgcn_s_setprio(1); _Pragma("unroll") for (int m = 0; m < 4; ++m) _Pragma("unroll") for (int n = 0; n < 2; ++n) _Pragma("unroll") for (int k = 0; k < 2; ++k) \
;         acc[ai][bj][m][n] = __builtin_amdgcn_mfma_f32_16x16x32_bf16(Bt[n][k], At[m][k], acc[ai][bj][m][n], 0, 0, 0); __builtin_amdgcn_s_setprio(0); } while (0)
; #define PG8_WAIT_V(n) asm volatile("s_waitcnt vmcnt(" #n ")" ::: "memory")
; #define PG8_WAIT_L(n) asm volatile("s_waitcnt lgkmcnt(" #n ")" ::: "memory")
; #define PG8_BAR __builtin_amdgcn_s_barrier()
; #define PG8_SCHED __builtin_amdgcn_sched_barrier(0)
; template <class Epi, class Sched, bool ATILE = false>
; __device__ __forceinline__ void gemm_phase(LAS unsigned char* lds, const Gemm g, const Sched& S, const Epi& E) {
;     ...
;             PG8_WAIT_V(6); PG8_BAR; PG8_MMA(1, 1, At, B1); PG8_BAR;
;             PG8_LDB(B0, 1, 0); PG8_SCHED; PG8_LDA(At, 1, 0); PG8_STAGE(PG8_SA(0, 1), a2 + hstepA, voffA);
;             PG8_WAIT_L(8); PG8_BAR; PG8_WAIT_L(0); PG8_MMA(0, 0, At, B0); PG8_BAR; PG8_SCHED;
;             PG8_LDB(B1, 1, 1); PG8_STAGE(PG8_SB(1, 0), b3, voffB);
;             PG8_BAR; PG8_WAIT_L(0); PG8_MMA(0, 1, At, B1); PG8_BAR;
	s_setprio 1
	v_mfma_f32_16x16x32_bf16 v[76:79], v[228:231], v[144:147], v[76:79]
	v_mfma_f32_16x16x32_bf16 v[72:75], v[236:239], v[144:147], v[72:75]
	v_mfma_f32_16x16x32_bf16 v[88:91], v[228:231], v[200:203], v[88:91]
	v_mfma_f32_16x16x32_bf16 v[80:83], v[236:239], v[200:203], v[80:83]
	v_mfma_f32_16x16x32_bf16 v[104:107], v[228:231], v[208:211], v[104:107]
	v_mfma_f32_16x16x32_bf16 v[96:99], v[236:239], v[208:211], v[96:99]
	v_mfma_f32_16x16x32_bf16 v[120:123], v[228:231], v[220:223], v[120:123]
	v_mfma_f32_16x16x32_bf16 v[124:127], v[236:239], v[220:223], v[124:127]
	v_mfma_f32_16x16x32_bf16 v[76:79], v[232:235], v[148:151], v[76:79]
	v_mfma_f32_16x16x32_bf16 v[72:75], v[240:243], v[148:151], v[72:75]
	v_mfma_f32_16x16x32_bf16 v[88:91], v[232:235], v[204:207], v[88:91]
	v_mfma_f32_16x16x32_bf16 v[80:83], v[240:243], v[204:207], v[80:83]
	v_mfma_f32_16x16x32_bf16 v[104:107], v[232:235], v[212:215], v[104:107]
	v_mfma_f32_16x16x32_bf16 v[96:99], v[240:243], v[212:215], v[96:99]
	v_mfma_f32_16x16x32_bf16 v[120:123], v[232:235], v[224:227], v[120:123]
	v_mfma_f32_16x16x32_bf16 v[124:127], v[240:243], v[224:227], v[124:127]
	s_setprio 0
	s_barrier
	s_add_i32 s63, 0, 0x18000
	v_add_u32_e32 v140, s63, v161
	ds_read_b128 v[128:131], v140
	ds_read_b128 v[132:135], v140 offset:1024
	ds_read_b128 v[136:139], v140 offset:2048
	ds_read_b128 v[140:143], v140 offset:3072
	s_add_u32 s30, s30, 0x4000
	s_addc_u32 s31, s31, 0
	s_mov_b32 m0, s36
	ds_read_b128 v[144:147], v167 offset:32768
	ds_read_b128 v[148:151], v167 offset:33792
	ds_read_b128 v[200:203], v167 offset:34816
	ds_read_b128 v[204:207], v167 offset:35840
	ds_read_b128 v[208:211], v167 offset:36864
	ds_read_b128 v[212:215], v167 offset:37888
	ds_read_b128 v[220:223], v167 offset:38912
	ds_read_b128 v[224:227], v167 offset:39936
	global_load_lds_dwordx4 v168, s[30:31]
	s_mov_b32 m0, s37
	s_nop 0
	global_load_lds_dwordx4 v172, s[30:31]
	s_waitcnt lgkmcnt(8)
	s_barrier
	s_waitcnt lgkmcnt(0)
	s_setprio 1
	s_waitcnt lgkmcnt(0)
	v_mfma_f32_16x16x32_bf16 v[0:3], v[128:131], v[144:147], v[0:3]
	v_mfma_f32_16x16x32_bf16 v[4:7], v[136:139], v[144:147], v[4:7]
	v_mfma_f32_16x16x32_bf16 v[44:47], v[128:131], v[200:203], v[44:47]
	v_mfma_f32_16x16x32_bf16 v[36:39], v[136:139], v[200:203], v[36:39]
	v_mfma_f32_16x16x32_bf16 v[52:55], v[128:131], v[208:211], v[52:55]
	v_mfma_f32_16x16x32_bf16 v[48:51], v[136:139], v[208:211], v[48:51]
	v_mfma_f32_16x16x32_bf16 v[92:95], v[128:131], v[220:223], v[92:95]
	v_mfma_f32_16x16x32_bf16 v[84:87], v[136:139], v[220:223], v[84:87]
	v_mfma_f32_16x16x32_bf16 v[0:3], v[132:135], v[148:151], v[0:3]
	v_mfma_f32_16x16x32_bf16 v[4:7], v[140:143], v[148:151], v[4:7]
	v_mfma_f32_16x16x32_bf16 v[44:47], v[132:135], v[204:207], v[44:47]
	v_mfma_f32_16x16x32_bf16 v[36:39], v[140:143], v[204:207], v[36:39]
	v_mfma_f32_16x16x32_bf16 v[52:55], v[132:135], v[212:215], v[52:55]
	v_mfma_f32_16x16x32_bf16 v[48:51], v[140:143], v[212:215], v[48:51]
	v_mfma_f32_16x16x32_bf16 v[92:95], v[132:135], v[224:227], v[92:95]
	v_mfma_f32_16x16x32_bf16 v[84:87], v[140:143], v[224:227], v[84:87]
	s_setprio 0
	s_barrier
	s_add_i32 s30, 0, 0x1c000
	s_add_i32 s31, s63, s33
	v_add_u32_e32 v219, s30, v161
	s_mov_b32 m0, s31
	ds_read_b128 v[228:231], v219
	ds_read_b128 v[232:235], v219 offset:1024
	ds_read_b128 v[236:239], v219 offset:2048
	ds_read_b128 v[240:243], v219 offset:3072
	global_load_lds_dwordx4 v170, s[98:99]
	s_add_i32 m0, s31, 0x2000
	s_nop 0
	global_load_lds_dwordx4 v174, s[98:99]
	s_barrier
	s_waitcnt lgkmcnt(0)
	s_setprio 1
	s_waitcnt lgkmcnt(0)
	v_mfma_f32_16x16x32_bf16 v[12:15], v[228:231], v[144:147], v[12:15]
	v_mfma_f32_16x16x32_bf16 v[8:11], v[236:239], v[144:147], v[8:11]
	v_mfma_f32_16x16x32_bf16 v[24:27], v[228:231], v[200:203], v[24:27]
	v_mfma_f32_16x16x32_bf16 v[16:19], v[236:239], v[200:203], v[16:19]
	v_mfma_f32_16x16x32_bf16 v[40:43], v[228:231], v[208:211], v[40:43]
	v_mfma_f32_16x16x32_bf16 v[32:35], v[236:239], v[208:211], v[32:35]
	v_mfma_f32_16x16x32_bf16 v[56:59], v[228:231], v[220:223], v[56:59]
	v_mfma_f32_16x16x32_bf16 v[60:63], v[236:239], v[220:223], v[60:63]
	v_mfma_f32_16x16x32_bf16 v[12:15], v[232:235], v[148:151], v[12:15]
	v_mfma_f32_16x16x32_bf16 v[8:11], v[240:243], v[148:151], v[8:11]
	v_mfma_f32_16x16x32_bf16 v[24:27], v[232:235], v[204:207], v[24:27]
	v_mfma_f32_16x16x32_bf16 v[16:19], v[240:243], v[204:207], v[16:19]
	v_mfma_f32_16x16x32_bf16 v[40:43], v[232:235], v[212:215], v[40:43]
	v_mfma_f32_16x16x32_bf16 v[32:35], v[240:243], v[212:215], v[32:35]
	v_mfma_f32_16x16x32_bf16 v[56:59], v[232:235], v[224:227], v[56:59]
	v_mfma_f32_16x16x32_bf16 v[60:63], v[240:243], v[224:227], v[60:63]
	s_setprio 0
	s_barrier
	s_mov_b32 m0, s39
	ds_read_b128 v[144:147], v167 offset:49152
	ds_read_b128 v[148:151], v167 offset:50176
	ds_read_b128 v[200:203], v167 offset:51200
	ds_read_b128 v[204:207], v167 offset:52224
	ds_read_b128 v[208:211], v167 offset:53248
	ds_read_b128 v[212:215], v167 offset:54272
	ds_read_b128 v[220:223], v167 offset:55296
	ds_read_b128 v[224:227], v167 offset:56320
	global_load_lds_dwordx4 v168, s[28:29]
	s_mov_b32 m0, s40
	s_nop 0
	global_load_lds_dwordx4 v172, s[28:29]
	s_barrier
; __device__ __forceinline__ float bflo(unsigned w) { return __uint_as_float(w << 16); }
; __device__ __forceinline__ float bfhi(unsigned w) { return __uint_as_float(w & 0xffff0000u); }
; #define PG8_STAGE(bufoff, gbase, voff) do { _Pragma("unroll") for (int _i = 0; _i < 2; ++_i) \
;         __builtin_amdgcn_global_load_lds((const unsigned*)((const char*)(gbase) + (voff)[_i]), (LAS unsigned*)(lds + (bufoff) + ldsw + _i * 8192), 16, 0, 0); } while (0)
; #define PG8_MMA(ai, bj, At, Bt) do { __builtin_amdgcn_s_setprio(1); _Pragma("unroll") for (int m = 0; m < 4; ++m) _Pragma("unroll") for (int n = 0; n < 2; ++n) _Pragma("unroll") for (int k = 0; k < 2; ++k) \
;         acc[ai][bj][m][n] = __builtin_amdgcn_mfma_f32_16x16x32_bf16(Bt[n][k], At[m][k], acc[ai][bj][m][n], 0, 0, 0); __builtin_amdgcn_s_setprio(0); } while (0)
; #define PG8_WAIT_V(n) asm volatile("s_waitcnt vmcnt(" #n ")" ::: "memory")
; #define PG8_WAIT_L(n) asm volatile("s_waitcnt lgkmcnt(" #n ")" ::: "memory")
; #define PG8_BAR __builtin_amdgcn_s_barrier()
; #define PG8_SCHED __builtin_amdgcn_sched_barrier(0)
; template <class Epi, class Sched, bool ATILE = false>
; __device__ __forceinline__ void gemm_phase(LAS unsigned char* lds, const Gemm g, const Sched& S, const Epi& E) {
;     ...
;             PG8_BAR; PG8_WAIT_L(0); PG8_MMA(1, 0, At, B0); PG8_BAR; PG8_SCHED;
;             PG8_STAGE(PG8_SB(1, 1), b3 + hstepB, voffB);
;             PG8_WAIT_V(6); PG8_BAR; PG8_MMA(1, 1, At, B1); PG8_BAR;
;         }
;         E(acc, cur, wr, wc, fr, fq);
;     __device__ __forceinline__ void operator()(const f32x4 (&acc)[2][2][4][2], const Unit& u, int wr, int wc, int fr, int fq) const {
;     ...
;                     const f32x4 v0 = (f32x4){bflo(x.x), bfhi(x.x), bflo(x.y), bfhi(x.y)} + alpha * acc[ai][bj][m][0];
;                     const f32x4 v1 = (f32x4){bflo(x.z), bfhi(x.z), bflo(x.w), bfhi(x.w)} + alpha * acc[ai][bj][m][1];
	s_waitcnt lgkmcnt(0)
	s_setprio 1
	s_waitcnt lgkmcnt(0)
	v_mfma_f32_16x16x32_bf16 v[64:67], v[128:131], v[144:147], v[64:67]
	v_mfma_f32_16x16x32_bf16 v[108:111], v[128:131], v[200:203], v[108:111]
	v_mfma_f32_16x16x32_bf16 v[116:119], v[128:131], v[208:211], v[116:119]
	v_mfma_f32_16x16x32_bf16 v[20:23], v[128:131], v[220:223], v[20:23]
	v_mfma_f32_16x16x32_bf16 v[64:67], v[132:135], v[148:151], v[64:67]
	v_mfma_f32_16x16x32_bf16 v[68:71], v[136:139], v[144:147], v[68:71]
	v_mfma_f32_16x16x32_bf16 v[108:111], v[132:135], v[204:207], v[108:111]
	v_mfma_f32_16x16x32_bf16 v[100:103], v[136:139], v[200:203], v[100:103]
	v_mfma_f32_16x16x32_bf16 v[116:119], v[132:135], v[212:215], v[116:119]
	v_mfma_f32_16x16x32_bf16 v[112:115], v[136:139], v[208:211], v[112:115]
	v_mfma_f32_16x16x32_bf16 v[132:135], v[132:135], v[224:227], v[20:23]
	v_mfma_f32_16x16x32_bf16 v[20:23], v[136:139], v[220:223], v[28:31]
	v_mfma_f32_16x16x32_bf16 v[68:71], v[140:143], v[148:151], v[68:71]
	v_mfma_f32_16x16x32_bf16 v[100:103], v[140:143], v[204:207], v[100:103]
	v_mfma_f32_16x16x32_bf16 v[112:115], v[140:143], v[212:215], v[112:115]
	v_mfma_f32_16x16x32_bf16 v[128:131], v[140:143], v[224:227], v[20:23]
	s_setprio 0
	s_barrier
	s_add_u32 s26, s26, 0x158080
	s_addc_u32 s27, s27, 0
	s_add_i32 s28, s30, s33
	s_mov_b32 m0, s28
	s_nop 0
	global_load_lds_dwordx4 v170, s[26:27]
	s_add_i32 m0, s28, 0x2000
	s_nop 0
	global_load_lds_dwordx4 v174, s[26:27]
	s_waitcnt vmcnt(6)
	s_barrier
	s_setprio 1
	v_mfma_f32_16x16x32_bf16 v[20:23], v[228:231], v[144:147], v[76:79]
	v_mfma_f32_16x16x32_bf16 v[76:79], v[232:235], v[148:151], v[20:23]
	v_mfma_f32_16x16x32_bf16 v[20:23], v[236:239], v[144:147], v[72:75]
	v_mfma_f32_16x16x32_bf16 v[72:75], v[240:243], v[148:151], v[20:23]
	v_mfma_f32_16x16x32_bf16 v[20:23], v[228:231], v[200:203], v[88:91]
	v_mfma_f32_16x16x32_bf16 v[88:91], v[232:235], v[204:207], v[20:23]
	v_mfma_f32_16x16x32_bf16 v[20:23], v[236:239], v[200:203], v[80:83]
	v_mfma_f32_16x16x32_bf16 v[80:83], v[240:243], v[204:207], v[20:23]
	v_mfma_f32_16x16x32_bf16 v[20:23], v[228:231], v[208:211], v[104:107]
	v_mfma_f32_16x16x32_bf16 v[104:107], v[232:235], v[212:215], v[20:23]
	v_mfma_f32_16x16x32_bf16 v[20:23], v[236:239], v[208:211], v[96:99]
	v_mfma_f32_16x16x32_bf16 v[96:99], v[240:243], v[212:215], v[20:23]
	v_mfma_f32_16x16x32_bf16 v[20:23], v[228:231], v[220:223], v[120:123]
	v_mfma_f32_16x16x32_bf16 v[120:123], v[232:235], v[224:227], v[20:23]
	v_mfma_f32_16x16x32_bf16 v[20:23], v[236:239], v[220:223], v[124:127]
	v_mfma_f32_16x16x32_bf16 v[124:127], v[240:243], v[224:227], v[20:23]
	s_setprio 0
	s_barrier
	s_add_u32 s60, s60, 0x100
	s_addc_u32 s61, s61, 0
	s_add_u32 s24, s24, 0x10000
	s_addc_u32 s25, s25, 0
	s_cmp_ge_i32 s62, s59
	s_mov_b32 s26, s62
	s_cbranch_scc0 .LBB0_739
	v_pk_mul_f32 v[2:3], v[2:3], 0.5 op_sel_hi:[1,0]
	v_pk_mul_f32 v[0:1], v[0:1], 0.5 op_sel_hi:[1,0]
	v_pk_mul_f32 v[6:7], v[6:7], 0.5 op_sel_hi:[1,0]
	v_pk_mul_f32 v[4:5], v[4:5], 0.5 op_sel_hi:[1,0]
	v_pk_mul_f32 v[22:23], v[14:15], 0.5 op_sel_hi:[1,0]
	v_pk_mul_f32 v[20:21], v[12:13], 0.5 op_sel_hi:[1,0]
	v_pk_mul_f32 v[30:31], v[10:11], 0.5 op_sel_hi:[1,0]
	v_pk_mul_f32 v[28:29], v[8:9], 0.5 op_sel_hi:[1,0]
	v_pk_mul_f32 v[10:11], v[46:47], 0.5 op_sel_hi:[1,0]
	v_pk_mul_f32 v[8:9], v[44:45], 0.5 op_sel_hi:[1,0]
	v_pk_mul_f32 v[14:15], v[38:39], 0.5 op_sel_hi:[1,0]
	v_pk_mul_f32 v[12:13], v[36:37], 0.5 op_sel_hi:[1,0]
	v_pk_mul_f32 v[38:39], v[26:27], 0.5 op_sel_hi:[1,0]
	v_pk_mul_f32 v[36:37], v[24:25], 0.5 op_sel_hi:[1,0]
	v_pk_mul_f32 v[46:47], v[18:19], 0.5 op_sel_hi:[1,0]
	v_pk_mul_f32 v[44:45], v[16:17], 0.5 op_sel_hi:[1,0]
	v_pk_mul_f32 v[18:19], v[54:55], 0.5 op_sel_hi:[1,0]
	v_pk_mul_f32 v[16:17], v[52:53], 0.5 op_sel_hi:[1,0]
	v_pk_mul_f32 v[26:27], v[50:51], 0.5 op_sel_hi:[1,0]
	v_pk_mul_f32 v[24:25], v[48:49], 0.5 op_sel_hi:[1,0]
	v_pk_mul_f32 v[50:51], v[42:43], 0.5 op_sel_hi:[1,0]
	v_pk_mul_f32 v[48:49], v[40:41], 0.5 op_sel_hi:[1,0]
	v_pk_mul_f32 v[54:55], v[34:35], 0.5 op_sel_hi:[1,0]
	v_pk_mul_f32 v[52:53], v[32:33], 0.5 op_sel_hi:[1,0]
	v_pk_mul_f32 v[34:35], v[94:95], 0.5 op_sel_hi:[1,0]
	v_pk_mul_f32 v[32:33], v[92:93], 0.5 op_sel_hi:[1,0]
	v_pk_mul_f32 v[42:43], v[86:87], 0.5 op_sel_hi:[1,0]
	v_pk_mul_f32 v[40:41], v[84:85], 0.5 op_sel_hi:[1,0]
	v_pk_mul_f32 v[58:59], v[58:59], 0.5 op_sel_hi:[1,0]
	v_pk_mul_f32 v[56:57], v[56:57], 0.5 op_sel_hi:[1,0]
	v_pk_mul_f32 v[62:63], v[62:63], 0.5 op_sel_hi:[1,0]
	v_pk_mul_f32 v[60:61], v[60:61], 0.5 op_sel_hi:[1,0]
	v_pk_mul_f32 v[66:67], v[66:67], 0.5 op_sel_hi:[1,0]
	v_pk_mul_f32 v[64:65], v[64:65], 0.5 op_sel_hi:[1,0]
	v_pk_mul_f32 v[70:71], v[70:71], 0.5 op_sel_hi:[1,0]
	v_pk_mul_f32 v[68:69], v[68:69], 0.5 op_sel_hi:[1,0]
	v_pk_mul_f32 v[86:87], v[78:79], 0.5 op_sel_hi:[1,0]
	v_pk_mul_f32 v[84:85], v[76:77], 0.5 op_sel_hi:[1,0]
	v_pk_mul_f32 v[94:95], v[74:75], 0.5 op_sel_hi:[1,0]
	v_pk_mul_f32 v[92:93], v[72:73], 0.5 op_sel_hi:[1,0]
	v_pk_mul_f32 v[74:75], v[110:111], 0.5 op_sel_hi:[1,0]
	v_pk_mul_f32 v[72:73], v[108:109], 0.5 op_sel_hi:[1,0]
	v_pk_mul_f32 v[78:79], v[102:103], 0.5 op_sel_hi:[1,0]
	v_pk_mul_f32 v[76:77], v[100:101], 0.5 op_sel_hi:[1,0]
	v_pk_mul_f32 v[102:103], v[90:91], 0.5 op_sel_hi:[1,0]
	v_pk_mul_f32 v[100:101], v[88:89], 0.5 op_sel_hi:[1,0]
	v_pk_mul_f32 v[110:111], v[82:83], 0.5 op_sel_hi:[1,0]
	v_pk_mul_f32 v[108:109], v[80:81], 0.5 op_sel_hi:[1,0]
	v_pk_mul_f32 v[82:83], v[118:119], 0.5 op_sel_hi:[1,0]
	v_pk_mul_f32 v[80:81], v[116:117], 0.5 op_sel_hi:[1,0]
	v_pk_mul_f32 v[90:91], v[114:115], 0.5 op_sel_hi:[1,0]
	v_pk_mul_f32 v[88:89], v[112:113], 0.5 op_sel_hi:[1,0]
	v_pk_mul_f32 v[114:115], v[106:107], 0.5 op_sel_hi:[1,0]
	v_pk_mul_f32 v[112:113], v[104:105], 0.5 op_sel_hi:[1,0]
	v_pk_mul_f32 v[118:119], v[98:99], 0.5 op_sel_hi:[1,0]
	v_pk_mul_f32 v[116:117], v[96:97], 0.5 op_sel_hi:[1,0]
	v_pk_mul_f32 v[98:99], v[134:135], 0.5 op_sel_hi:[1,0]
	v_pk_mul_f32 v[96:97], v[132:133], 0.5 op_sel_hi:[1,0]
	v_pk_mul_f32 v[106:107], v[130:131], 0.5 op_sel_hi:[1,0]
	v_pk_mul_f32 v[104:105], v[128:129], 0.5 op_sel_hi:[1,0]
	v_pk_mul_f32 v[122:123], v[122:123], 0.5 op_sel_hi:[1,0]
	v_pk_mul_f32 v[120:121], v[120:121], 0.5 op_sel_hi:[1,0]
	v_pk_mul_f32 v[126:127], v[126:127], 0.5 op_sel_hi:[1,0]
	v_pk_mul_f32 v[124:125], v[124:125], 0.5 op_sel_hi:[1,0]
	s_branch .LBB0_744

; #define PG8_STAGE(bufoff, gbase, voff) do { _Pragma("unroll") for (int _i = 0; _i < 2; ++_i) \
;         __builtin_amdgcn_global_load_lds((const unsigned*)((const char*)(gbase) + (voff)[_i]), (LAS unsigned*)(lds + (bufoff) + ldsw + _i * 8192), 16, 0, 0); } while (0)
; #define PG8_LDA(dst, b, h) do { _Pragma("unroll") for (int m = 0; m < 4; ++m) _Pragma("unroll") for (int k = 0; k < 2; ++k) dst[m][k] = *(const LAS bf16x8*)(lds + PG8_SA(b, h) + aoff + m * 2048 + k * 1024); } while (0)
; #define PG8_LDB(dst, b, h) do { _Pragma("unroll") for (int n = 0; n < 2; ++n) _Pragma("unroll") for (int k = 0; k < 2; ++k) dst[n][k] = *(const LAS bf16x8*)(lds + PG8_SB(b, h) + boff + n * 2048 + k * 1024); } while (0)
; #define PG8_MMA(ai, bj, At, Bt) do { __builtin_amdgcn_s_setprio(1); _Pragma("unroll") for (int m = 0; m < 4; ++m) _Pragma("unroll") for (int n = 0; n < 2; ++n) _Pragma("unroll") for (int k = 0; k < 2; ++k) \
;         acc[ai][bj][m][n] = __builtin_amdgcn_mfma_f32_16x16x32_bf16(Bt[n][k], At[m][k], acc[ai][bj][m][n], 0, 0, 0); __builtin_amdgcn_s_setprio(0); } while (0)
; #define PG8_WAIT_V(n) asm volatile("s_waitcnt vmcnt(" #n ")" ::: "memory")
; #define PG8_WAIT_L(n) asm volatile("s_waitcnt lgkmcnt(" #n ")" ::: "memory")
; template <class Epi, class Sched, bool ATILE = false>
; __device__ __forceinline__ void gemm_phase(LAS unsigned char* lds, const Gemm g, const Sched& S, const Epi& E) {
;     ...
;         for (int t = 0; t < nt; t += 2) {
;             const bool last = (t == nt - 2);
;             const char* a1 = cA + (size_t)(t + 1) * kstepA;
;             const char* a2 = last ? nA : cA + (size_t)(t + 2) * kstepA; const char* b2 = last ? nB : cB + (size_t)(t + 2) * kstep;
;             const char* a3 = a2 + kstepA; const char* b3 = b2 + kstep;
;             PG8_LDB(B0, 0, 0); PG8_SCHED; PG8_LDA(At, 0, 0); PG8_STAGE(PG8_SA(1, 1), a1 + hstepA, voffA);
;             PG8_WAIT_L(8); PG8_BAR; PG8_WAIT_L(0); PG8_MMA(0, 0, At, B0); PG8_BAR; PG8_SCHED;
;             PG8_LDB(B1, 0, 1); PG8_STAGE(PG8_SB(0, 0), b2, voffB);
;             PG8_BAR; PG8_WAIT_L(0); PG8_MMA(0, 1, At, B1); PG8_BAR;
;             PG8_LDA(At, 0, 1); PG8_STAGE(PG8_SA(0, 0), a2, voffA);
;             PG8_BAR; PG8_WAIT_L(0); PG8_MMA(1, 0, At, B0); PG8_BAR; PG8_SCHED;
;             PG8_STAGE(PG8_SB(0, 1), b2 + hstepB, voffB);
;             PG8_WAIT_V(6); PG8_BAR; PG8_MMA(1, 1, At, B1); PG8_BAR;
.LBB0_895:
	ds_read_b128 v[32:35], v165
	ds_read_b128 v[36:39], v165 offset:1024
	ds_read_b128 v[178:181], v165 offset:2048
	ds_read_b128 v[182:185], v165 offset:3072
	s_add_i32 s88, s73, 2
	s_add_u32 s84, s12, 0xfff80080
	s_addc_u32 s85, s13, -1
	s_cmp_eq_u32 s53, s73
	s_cselect_b32 s87, s11, s85
	s_cselect_b32 s86, s20, s84
	s_cselect_b32 s85, s41, s63
	s_cselect_b32 s84, s52, s62
	s_add_i32 m0, s35, 0xc000
	ds_read_b128 v[192:195], v167
	ds_read_b128 v[196:199], v167 offset:1024
	ds_read_b128 v[200:203], v167 offset:2048
	ds_read_b128 v[204:207], v167 offset:3072
	ds_read_b128 v[208:211], v167 offset:4096
	ds_read_b128 v[212:215], v167 offset:5120
	ds_read_b128 v[216:219], v167 offset:6144
	ds_read_b128 v[220:223], v167 offset:7168
	global_load_lds_dwordx4 v170, s[12:13]
	s_add_i32 m0, s35, 0xe000
	s_nop 0
	global_load_lds_dwordx4 v172, s[12:13]
	s_waitcnt lgkmcnt(8)
	s_barrier
	s_waitcnt lgkmcnt(0)
	s_setprio 1
	s_waitcnt lgkmcnt(0)
	v_mfma_f32_16x16x32_bf16 v[132:135], v[32:35], v[192:195], v[132:135]
	v_mfma_f32_16x16x32_bf16 v[128:131], v[178:181], v[192:195], v[128:131]
	v_mfma_f32_16x16x32_bf16 v[116:119], v[32:35], v[200:203], v[116:119]
	v_mfma_f32_16x16x32_bf16 v[112:115], v[178:181], v[200:203], v[112:115]
	v_mfma_f32_16x16x32_bf16 v[100:103], v[32:35], v[208:211], v[100:103]
	v_mfma_f32_16x16x32_bf16 v[96:99], v[178:181], v[208:211], v[96:99]
	v_mfma_f32_16x16x32_bf16 v[84:87], v[32:35], v[216:219], v[84:87]
	v_mfma_f32_16x16x32_bf16 v[80:83], v[178:181], v[216:219], v[80:83]
	v_mfma_f32_16x16x32_bf16 v[132:135], v[36:39], v[196:199], v[132:135]
	v_mfma_f32_16x16x32_bf16 v[128:131], v[182:185], v[196:199], v[128:131]
	v_mfma_f32_16x16x32_bf16 v[116:119], v[36:39], v[204:207], v[116:119]
	v_mfma_f32_16x16x32_bf16 v[112:115], v[182:185], v[204:207], v[112:115]
	v_mfma_f32_16x16x32_bf16 v[100:103], v[36:39], v[212:215], v[100:103]
	v_mfma_f32_16x16x32_bf16 v[96:99], v[182:185], v[212:215], v[96:99]
	v_mfma_f32_16x16x32_bf16 v[84:87], v[36:39], v[220:223], v[84:87]
	v_mfma_f32_16x16x32_bf16 v[80:83], v[182:185], v[220:223], v[80:83]
	s_setprio 0
	s_barrier
	s_add_i32 s73, s43, s31
	s_add_u32 s98, s84, s22
	s_addc_u32 s99, s85, s23
	s_mov_b32 m0, s73
	ds_read_b128 v[224:227], v186
	ds_read_b128 v[228:231], v186 offset:1024
	ds_read_b128 v[232:235], v186 offset:2048
	ds_read_b128 v[236:239], v186 offset:3072
	global_load_lds_dwordx4 v138, s[84:85]
	s_add_i32 m0, s73, 0x2000
	s_nop 0
	global_load_lds_dwordx4 v142, s[84:85]
	s_barrier
	s_waitcnt lgkmcnt(0)
	s_setprio 1
	s_waitcnt lgkmcnt(0)
	v_mfma_f32_16x16x32_bf16 v[124:127], v[224:227], v[192:195], v[124:127]
	v_mfma_f32_16x16x32_bf16 v[120:123], v[232:235], v[192:195], v[120:123]
	v_mfma_f32_16x16x32_bf16 v[108:111], v[224:227], v[200:203], v[108:111]
	v_mfma_f32_16x16x32_bf16 v[104:107], v[232:235], v[200:203], v[104:107]
	v_mfma_f32_16x16x32_bf16 v[92:95], v[224:227], v[208:211], v[92:95]
	v_mfma_f32_16x16x32_bf16 v[88:91], v[232:235], v[208:211], v[88:91]
	v_mfma_f32_16x16x32_bf16 v[76:79], v[224:227], v[216:219], v[76:79]
	v_mfma_f32_16x16x32_bf16 v[72:75], v[232:235], v[216:219], v[72:75]
	v_mfma_f32_16x16x32_bf16 v[124:127], v[228:231], v[196:199], v[124:127]
	v_mfma_f32_16x16x32_bf16 v[120:123], v[236:239], v[196:199], v[120:123]
	v_mfma_f32_16x16x32_bf16 v[108:111], v[228:231], v[204:207], v[108:111]
	v_mfma_f32_16x16x32_bf16 v[104:107], v[236:239], v[204:207], v[104:107]
	v_mfma_f32_16x16x32_bf16 v[92:95], v[228:231], v[212:215], v[92:95]
	v_mfma_f32_16x16x32_bf16 v[88:91], v[236:239], v[212:215], v[88:91]
	v_mfma_f32_16x16x32_bf16 v[76:79], v[228:231], v[220:223], v[76:79]
	v_mfma_f32_16x16x32_bf16 v[72:75], v[236:239], v[220:223], v[72:75]
	s_setprio 0
	s_barrier
	s_mov_b32 m0, s35
	s_add_u32 s100, s86, s22
	s_addc_u32 s101, s87, s23
	ds_read_b128 v[192:195], v167 offset:16384
	ds_read_b128 v[196:199], v167 offset:17408
	ds_read_b128 v[200:203], v167 offset:18432
	ds_read_b128 v[204:207], v167 offset:19456
	ds_read_b128 v[208:211], v167 offset:20480
	ds_read_b128 v[212:215], v167 offset:21504
	ds_read_b128 v[216:219], v167 offset:22528
	ds_read_b128 v[220:223], v167 offset:23552
	global_load_lds_dwordx4 v136, s[86:87]
	s_mov_b32 m0, s37
	s_nop 0
	global_load_lds_dwordx4 v140, s[86:87]
	s_barrier
	s_waitcnt lgkmcnt(0)
	s_setprio 1
	s_waitcnt lgkmcnt(0)
	v_mfma_f32_16x16x32_bf16 v[68:71], v[32:35], v[192:195], v[68:71]
	v_mfma_f32_16x16x32_bf16 v[64:67], v[178:181], v[192:195], v[64:67]
	v_mfma_f32_16x16x32_bf16 v[52:55], v[32:35], v[200:203], v[52:55]
	v_mfma_f32_16x16x32_bf16 v[48:51], v[178:181], v[200:203], v[48:51]
	v_mfma_f32_16x16x32_bf16 v[28:31], v[32:35], v[208:211], v[28:31]
	v_mfma_f32_16x16x32_bf16 v[24:27], v[178:181], v[208:211], v[24:27]
	v_mfma_f32_16x16x32_bf16 v[12:15], v[32:35], v[216:219], v[12:15]
	v_mfma_f32_16x16x32_bf16 v[8:11], v[178:181], v[216:219], v[8:11]
	v_mfma_f32_16x16x32_bf16 v[68:71], v[36:39], v[196:199], v[68:71]
	v_mfma_f32_16x16x32_bf16 v[64:67], v[182:185], v[196:199], v[64:67]
	v_mfma_f32_16x16x32_bf16 v[52:55], v[36:39], v[204:207], v[52:55]
	v_mfma_f32_16x16x32_bf16 v[48:51], v[182:185], v[204:207], v[48:51]
	v_mfma_f32_16x16x32_bf16 v[28:31], v[36:39], v[212:215], v[28:31]
	v_mfma_f32_16x16x32_bf16 v[24:27], v[182:185], v[212:215], v[24:27]
	v_mfma_f32_16x16x32_bf16 v[12:15], v[36:39], v[220:223], v[12:15]
	v_mfma_f32_16x16x32_bf16 v[8:11], v[182:185], v[220:223], v[8:11]
	s_setprio 0
	s_barrier
	s_add_u32 vcc_lo, s84, 0x80000
	s_addc_u32 vcc_hi, s85, 0
	s_add_i32 s73, s56, s31
	v_lshl_add_u64 v[32:33], vcc, 0, v[138:139]
	s_mov_b32 m0, s73
	s_nop 0
	global_load_lds_dwordx4 v[32:33], off
	v_lshl_add_u64 v[32:33], vcc, 0, v[142:143]
	s_add_i32 m0, s73, 0x2000
	s_nop 0
	global_load_lds_dwordx4 v[32:33], off
	s_waitcnt vmcnt(6)
	s_barrier
; #define PG8_STAGE(bufoff, gbase, voff) do { _Pragma("unroll") for (int _i = 0; _i < 2; ++_i) \
;         __builtin_amdgcn_global_load_lds((const unsigned*)((const char*)(gbase) + (voff)[_i]), (LAS unsigned*)(lds + (bufoff) + ldsw + _i * 8192), 16, 0, 0); } while (0)
; #define PG8_LDA(dst, b, h) do { _Pragma("unroll") for (int m = 0; m < 4; ++m) _Pragma("unroll") for (int k = 0; k < 2; ++k) dst[m][k] = *(const LAS bf16x8*)(lds + PG8_SA(b, h) + aoff + m * 2048 + k * 1024); } while (0)
; #define PG8_LDB(dst, b, h) do { _Pragma("unroll") for (int n = 0; n < 2; ++n) _Pragma("unroll") for (int k = 0; k < 2; ++k) dst[n][k] = *(const LAS bf16x8*)(lds + PG8_SB(b, h) + boff + n * 2048 + k * 1024); } while (0)
; #define PG8_MMA(ai, bj, At, Bt) do { __builtin_amdgcn_s_setprio(1); _Pragma("unroll") for (int m = 0; m < 4; ++m) _Pragma("unroll") for (int n = 0; n < 2; ++n) _Pragma("unroll") for (int k = 0; k < 2; ++k) \
;         acc[ai][bj][m][n] = __builtin_amdgcn_mfma_f32_16x16x32_bf16(Bt[n][k], At[m][k], acc[ai][bj][m][n], 0, 0, 0); __builtin_amdgcn_s_setprio(0); } while (0)
; #define PG8_WAIT_V(n) asm volatile("s_waitcnt vmcnt(" #n ")" ::: "memory")
; #define PG8_WAIT_L(n) asm volatile("s_waitcnt lgkmcnt(" #n ")" ::: "memory")
; #define PG8_BAR __builtin_amdgcn_s_barrier()
; #define PG8_SCHED __builtin_amdgcn_sched_barrier(0)
; template <class Epi, class Sched, bool ATILE = false>
; __device__ __forceinline__ void gemm_phase(LAS unsigned char* lds, const Gemm g, const Sched& S, const Epi& E) {
;     ...
;             PG8_WAIT_V(6); PG8_BAR; PG8_MMA(1, 1, At, B1); PG8_BAR;
;             PG8_LDB(B0, 1, 0); PG8_SCHED; PG8_LDA(At, 1, 0); PG8_STAGE(PG8_SA(0, 1), a2 + hstepA, voffA);
;             PG8_WAIT_L(8); PG8_BAR; PG8_WAIT_L(0); PG8_MMA(0, 0, At, B0); PG8_BAR; PG8_SCHED;
;             PG8_LDB(B1, 1, 1); PG8_STAGE(PG8_SB(1, 0), b3, voffB);
;             PG8_BAR; PG8_WAIT_L(0); PG8_MMA(0, 1, At, B1); PG8_BAR;
	s_setprio 1
	v_mfma_f32_16x16x32_bf16 v[44:47], v[224:227], v[200:203], v[44:47]
	v_mfma_f32_16x16x32_bf16 v[40:43], v[232:235], v[200:203], v[40:43]
	v_mfma_f32_16x16x32_bf16 v[20:23], v[224:227], v[208:211], v[20:23]
	v_mfma_f32_16x16x32_bf16 v[16:19], v[232:235], v[208:211], v[16:19]
	v_mfma_f32_16x16x32_bf16 v[4:7], v[224:227], v[216:219], v[4:7]
	v_mfma_f32_16x16x32_bf16 v[0:3], v[232:235], v[216:219], v[0:3]
	v_mfma_f32_16x16x32_bf16 v[32:35], v[224:227], v[192:195], v[60:63]
	v_mfma_f32_16x16x32_bf16 v[36:39], v[232:235], v[192:195], v[56:59]
	v_mfma_f32_16x16x32_bf16 v[44:47], v[228:231], v[204:207], v[44:47]
	v_mfma_f32_16x16x32_bf16 v[40:43], v[236:239], v[204:207], v[40:43]
	v_mfma_f32_16x16x32_bf16 v[20:23], v[228:231], v[212:215], v[20:23]
	v_mfma_f32_16x16x32_bf16 v[16:19], v[236:239], v[212:215], v[16:19]
	v_mfma_f32_16x16x32_bf16 v[4:7], v[228:231], v[220:223], v[4:7]
	v_mfma_f32_16x16x32_bf16 v[0:3], v[236:239], v[220:223], v[0:3]
	v_mfma_f32_16x16x32_bf16 v[32:35], v[228:231], v[196:199], v[32:35]
	v_mfma_f32_16x16x32_bf16 v[36:39], v[236:239], v[196:199], v[36:39]
	s_setprio 0
	s_barrier
	s_add_i32 s73, 0, 0x18000
	v_add_u32_e32 v144, s73, v161
	ds_read_b128 v[56:59], v144
	ds_read_b128 v[60:63], v144 offset:1024
	ds_read_b128 v[178:181], v144 offset:2048
	ds_read_b128 v[182:185], v144 offset:3072
	s_add_u32 s86, s86, 0x80000
	s_addc_u32 s87, s87, 0
	s_mov_b32 m0, s39
	ds_read_b128 v[192:195], v167 offset:32768
	ds_read_b128 v[196:199], v167 offset:33792
	ds_read_b128 v[200:203], v167 offset:34816
	ds_read_b128 v[204:207], v167 offset:35840
	ds_read_b128 v[208:211], v167 offset:36864
	ds_read_b128 v[212:215], v167 offset:37888
	ds_read_b128 v[216:219], v167 offset:38912
	ds_read_b128 v[220:223], v167 offset:39936
	global_load_lds_dwordx4 v136, s[86:87]
	s_mov_b32 m0, s97
	s_nop 0
	global_load_lds_dwordx4 v140, s[86:87]
	s_waitcnt lgkmcnt(8)
	s_barrier
	s_waitcnt lgkmcnt(0)
	s_setprio 1
	s_waitcnt lgkmcnt(0)
	v_mfma_f32_16x16x32_bf16 v[132:135], v[56:59], v[192:195], v[132:135]
	v_mfma_f32_16x16x32_bf16 v[128:131], v[178:181], v[192:195], v[128:131]
	v_mfma_f32_16x16x32_bf16 v[116:119], v[56:59], v[200:203], v[116:119]
	v_mfma_f32_16x16x32_bf16 v[112:115], v[178:181], v[200:203], v[112:115]
	v_mfma_f32_16x16x32_bf16 v[100:103], v[56:59], v[208:211], v[100:103]
	v_mfma_f32_16x16x32_bf16 v[96:99], v[178:181], v[208:211], v[96:99]
	v_mfma_f32_16x16x32_bf16 v[84:87], v[56:59], v[216:219], v[84:87]
	v_mfma_f32_16x16x32_bf16 v[80:83], v[178:181], v[216:219], v[80:83]
	v_mfma_f32_16x16x32_bf16 v[132:135], v[60:63], v[196:199], v[132:135]
	v_mfma_f32_16x16x32_bf16 v[128:131], v[182:185], v[196:199], v[128:131]
	v_mfma_f32_16x16x32_bf16 v[116:119], v[60:63], v[204:207], v[116:119]
	v_mfma_f32_16x16x32_bf16 v[112:115], v[182:185], v[204:207], v[112:115]
	v_mfma_f32_16x16x32_bf16 v[100:103], v[60:63], v[212:215], v[100:103]
	v_mfma_f32_16x16x32_bf16 v[96:99], v[182:185], v[212:215], v[96:99]
	v_mfma_f32_16x16x32_bf16 v[84:87], v[60:63], v[220:223], v[84:87]
	v_mfma_f32_16x16x32_bf16 v[80:83], v[182:185], v[220:223], v[80:83]
	s_setprio 0
	s_barrier
	s_add_i32 s86, 0, 0x1c000
	s_add_i32 s73, s73, s31
	v_add_u32_e32 v144, s86, v161
	s_mov_b32 m0, s73
	ds_read_b128 v[224:227], v144
	ds_read_b128 v[228:231], v144 offset:1024
	ds_read_b128 v[232:235], v144 offset:2048
	ds_read_b128 v[236:239], v144 offset:3072
	global_load_lds_dwordx4 v138, s[98:99]
	s_add_i32 m0, s73, 0x2000
	s_nop 0
	global_load_lds_dwordx4 v142, s[98:99]
	s_barrier
; #define PG8_STAGE(bufoff, gbase, voff) do { _Pragma("unroll") for (int _i = 0; _i < 2; ++_i) \
;         __builtin_amdgcn_global_load_lds((const unsigned*)((const char*)(gbase) + (voff)[_i]), (LAS unsigned*)(lds + (bufoff) + ldsw + _i * 8192), 16, 0, 0); } while (0)
; #define PG8_LDA(dst, b, h) do { _Pragma("unroll") for (int m = 0; m < 4; ++m) _Pragma("unroll") for (int k = 0; k < 2; ++k) dst[m][k] = *(const LAS bf16x8*)(lds + PG8_SA(b, h) + aoff + m * 2048 + k * 1024); } while (0)
; #define PG8_MMA(ai, bj, At, Bt) do { __builtin_amdgcn_s_setprio(1); _Pragma("unroll") for (int m = 0; m < 4; ++m) _Pragma("unroll") for (int n = 0; n < 2; ++n) _Pragma("unroll") for (int k = 0; k < 2; ++k) \
;         acc[ai][bj][m][n] = __builtin_amdgcn_mfma_f32_16x16x32_bf16(Bt[n][k], At[m][k], acc[ai][bj][m][n], 0, 0, 0); __builtin_amdgcn_s_setprio(0); } while (0)
; #define PG8_WAIT_V(n) asm volatile("s_waitcnt vmcnt(" #n ")" ::: "memory")
; #define PG8_WAIT_L(n) asm volatile("s_waitcnt lgkmcnt(" #n ")" ::: "memory")
; #define PG8_BAR __builtin_amdgcn_s_barrier()
; #define PG8_SCHED __builtin_amdgcn_sched_barrier(0)
; template <class Epi, class Sched, bool ATILE = false>
; __device__ __forceinline__ void gemm_phase(LAS unsigned char* lds, const Gemm g, const Sched& S, const Epi& E) {
;     ...
;             PG8_BAR; PG8_WAIT_L(0); PG8_MMA(0, 1, At, B1); PG8_BAR;
;             PG8_LDA(At, 1, 1); PG8_STAGE(PG8_SA(1, 0), a3, voffA);
;             PG8_BAR; PG8_WAIT_L(0); PG8_MMA(1, 0, At, B0); PG8_BAR; PG8_SCHED;
;             PG8_STAGE(PG8_SB(1, 1), b3 + hstepB, voffB);
;             PG8_WAIT_V(6); PG8_BAR; PG8_MMA(1, 1, At, B1); PG8_BAR;
;         }
;         E(acc, cur, wr, wc, fr, fq);
;         if (!has_next) break;
	s_waitcnt lgkmcnt(0)
	s_setprio 1
	s_waitcnt lgkmcnt(0)
	v_mfma_f32_16x16x32_bf16 v[124:127], v[224:227], v[192:195], v[124:127]
	v_mfma_f32_16x16x32_bf16 v[120:123], v[232:235], v[192:195], v[120:123]
	v_mfma_f32_16x16x32_bf16 v[108:111], v[224:227], v[200:203], v[108:111]
	v_mfma_f32_16x16x32_bf16 v[104:107], v[232:235], v[200:203], v[104:107]
	v_mfma_f32_16x16x32_bf16 v[92:95], v[224:227], v[208:211], v[92:95]
	v_mfma_f32_16x16x32_bf16 v[88:91], v[232:235], v[208:211], v[88:91]
	v_mfma_f32_16x16x32_bf16 v[76:79], v[224:227], v[216:219], v[76:79]
	v_mfma_f32_16x16x32_bf16 v[72:75], v[232:235], v[216:219], v[72:75]
	v_mfma_f32_16x16x32_bf16 v[124:127], v[228:231], v[196:199], v[124:127]
	v_mfma_f32_16x16x32_bf16 v[120:123], v[236:239], v[196:199], v[120:123]
	v_mfma_f32_16x16x32_bf16 v[108:111], v[228:231], v[204:207], v[108:111]
	v_mfma_f32_16x16x32_bf16 v[104:107], v[236:239], v[204:207], v[104:107]
	v_mfma_f32_16x16x32_bf16 v[92:95], v[228:231], v[212:215], v[92:95]
	v_mfma_f32_16x16x32_bf16 v[88:91], v[236:239], v[212:215], v[88:91]
	v_mfma_f32_16x16x32_bf16 v[76:79], v[228:231], v[220:223], v[76:79]
	v_mfma_f32_16x16x32_bf16 v[72:75], v[236:239], v[220:223], v[72:75]
	s_setprio 0
	s_barrier
	s_mov_b32 m0, s4
	ds_read_b128 v[192:195], v167 offset:49152
	ds_read_b128 v[196:199], v167 offset:50176
	ds_read_b128 v[200:203], v167 offset:51200
	ds_read_b128 v[204:207], v167 offset:52224
	ds_read_b128 v[208:211], v167 offset:53248
	ds_read_b128 v[212:215], v167 offset:54272
	ds_read_b128 v[216:219], v167 offset:55296
	ds_read_b128 v[220:223], v167 offset:56320
	global_load_lds_dwordx4 v136, s[100:101]
	s_mov_b32 m0, s5
	s_nop 0
	global_load_lds_dwordx4 v140, s[100:101]
	s_barrier
	s_waitcnt lgkmcnt(0)
	s_setprio 1
	s_waitcnt lgkmcnt(0)
	v_mfma_f32_16x16x32_bf16 v[68:71], v[56:59], v[192:195], v[68:71]
	v_mfma_f32_16x16x32_bf16 v[64:67], v[178:181], v[192:195], v[64:67]
	v_mfma_f32_16x16x32_bf16 v[52:55], v[56:59], v[200:203], v[52:55]
	v_mfma_f32_16x16x32_bf16 v[48:51], v[178:181], v[200:203], v[48:51]
	v_mfma_f32_16x16x32_bf16 v[28:31], v[56:59], v[208:211], v[28:31]
	v_mfma_f32_16x16x32_bf16 v[24:27], v[178:181], v[208:211], v[24:27]
	v_mfma_f32_16x16x32_bf16 v[12:15], v[56:59], v[216:219], v[12:15]
	v_mfma_f32_16x16x32_bf16 v[8:11], v[178:181], v[216:219], v[8:11]
	v_mfma_f32_16x16x32_bf16 v[68:71], v[60:63], v[196:199], v[68:71]
	v_mfma_f32_16x16x32_bf16 v[64:67], v[182:185], v[196:199], v[64:67]
	v_mfma_f32_16x16x32_bf16 v[52:55], v[60:63], v[204:207], v[52:55]
	v_mfma_f32_16x16x32_bf16 v[48:51], v[182:185], v[204:207], v[48:51]
	v_mfma_f32_16x16x32_bf16 v[28:31], v[60:63], v[212:215], v[28:31]
	v_mfma_f32_16x16x32_bf16 v[24:27], v[182:185], v[212:215], v[24:27]
	v_mfma_f32_16x16x32_bf16 v[12:15], v[60:63], v[220:223], v[12:15]
	v_mfma_f32_16x16x32_bf16 v[8:11], v[182:185], v[220:223], v[8:11]
	s_setprio 0
	s_barrier
	s_add_u32 s84, s84, 0x80080
	s_addc_u32 s85, s85, 0
	s_add_i32 s73, s86, s31
	s_mov_b32 m0, s73
	s_nop 0
	global_load_lds_dwordx4 v138, s[84:85]
	s_add_i32 m0, s73, 0x2000
	s_nop 0
	global_load_lds_dwordx4 v142, s[84:85]
	s_waitcnt vmcnt(6)
	s_barrier
	s_setprio 1
	v_mfma_f32_16x16x32_bf16 v[32:35], v[224:227], v[192:195], v[32:35]
	v_mfma_f32_16x16x32_bf16 v[60:63], v[228:231], v[196:199], v[32:35]
	v_mfma_f32_16x16x32_bf16 v[32:35], v[232:235], v[192:195], v[36:39]
	v_mfma_f32_16x16x32_bf16 v[56:59], v[236:239], v[196:199], v[32:35]
	v_mfma_f32_16x16x32_bf16 v[32:35], v[224:227], v[200:203], v[44:47]
	v_mfma_f32_16x16x32_bf16 v[44:47], v[228:231], v[204:207], v[32:35]
	v_mfma_f32_16x16x32_bf16 v[32:35], v[232:235], v[200:203], v[40:43]
	v_mfma_f32_16x16x32_bf16 v[20:23], v[224:227], v[208:211], v[20:23]
	v_mfma_f32_16x16x32_bf16 v[16:19], v[232:235], v[208:211], v[16:19]
	v_mfma_f32_16x16x32_bf16 v[4:7], v[224:227], v[216:219], v[4:7]
	v_mfma_f32_16x16x32_bf16 v[0:3], v[232:235], v[216:219], v[0:3]
	v_mfma_f32_16x16x32_bf16 v[40:43], v[236:239], v[204:207], v[32:35]
	v_mfma_f32_16x16x32_bf16 v[20:23], v[228:231], v[212:215], v[20:23]
	v_mfma_f32_16x16x32_bf16 v[16:19], v[236:239], v[212:215], v[16:19]
	v_mfma_f32_16x16x32_bf16 v[4:7], v[228:231], v[220:223], v[4:7]
	v_mfma_f32_16x16x32_bf16 v[0:3], v[236:239], v[220:223], v[0:3]
	s_setprio 0
	s_barrier
	s_add_u32 s12, s12, 0x100
	s_addc_u32 s13, s13, 0
	s_add_u32 s62, s62, 0x100
	s_addc_u32 s63, s63, 0
	s_cmp_ge_i32 s88, s1
	s_mov_b32 s73, s88
	s_cbranch_scc0 .LBB0_895
	s_branch .LBB0_897

; #define PG8_STAGE(bufoff, gbase, voff) do { _Pragma("unroll") for (int _i = 0; _i < 2; ++_i) \
;         __builtin_amdgcn_global_load_lds((const unsigned*)((const char*)(gbase) + (voff)[_i]), (LAS unsigned*)(lds + (bufoff) + ldsw + _i * 8192), 16, 0, 0); } while (0)
; #define PG8_LDA(dst, b, h) do { _Pragma("unroll") for (int m = 0; m < 4; ++m) _Pragma("unroll") for (int k = 0; k < 2; ++k) dst[m][k] = *(const LAS bf16x8*)(lds + PG8_SA(b, h) + aoff + m * 2048 + k * 1024); } while (0)
; #define PG8_LDB(dst, b, h) do { _Pragma("unroll") for (int n = 0; n < 2; ++n) _Pragma("unroll") for (int k = 0; k < 2; ++k) dst[n][k] = *(const LAS bf16x8*)(lds + PG8_SB(b, h) + boff + n * 2048 + k * 1024); } while (0)
; #define PG8_MMA(ai, bj, At, Bt) do { __builtin_amdgcn_s_setprio(1); _Pragma("unroll") for (int m = 0; m < 4; ++m) _Pragma("unroll") for (int n = 0; n < 2; ++n) _Pragma("unroll") for (int k = 0; k < 2; ++k) \
;         acc[ai][bj][m][n] = __builtin_amdgcn_mfma_f32_16x16x32_bf16(Bt[n][k], At[m][k], acc[ai][bj][m][n], 0, 0, 0); __builtin_amdgcn_s_setprio(0); } while (0)
; #define PG8_WAIT_V(n) asm volatile("s_waitcnt vmcnt(" #n ")" ::: "memory")
; #define PG8_WAIT_L(n) asm volatile("s_waitcnt lgkmcnt(" #n ")" ::: "memory")
; template <class Epi, class Sched, bool ATILE = false>
; __device__ __forceinline__ void gemm_phase(LAS unsigned char* lds, const Gemm g, const Sched& S, const Epi& E) {
;     ...
;         for (int t = 0; t < nt; t += 2) {
;             const bool last = (t == nt - 2);
;             const char* a1 = cA + (size_t)(t + 1) * kstepA;
;             const char* a2 = last ? nA : cA + (size_t)(t + 2) * kstepA; const char* b2 = last ? nB : cB + (size_t)(t + 2) * kstep;
;             const char* a3 = a2 + kstepA; const char* b3 = b2 + kstep;
;             PG8_LDB(B0, 0, 0); PG8_SCHED; PG8_LDA(At, 0, 0); PG8_STAGE(PG8_SA(1, 1), a1 + hstepA, voffA);
;             PG8_WAIT_L(8); PG8_BAR; PG8_WAIT_L(0); PG8_MMA(0, 0, At, B0); PG8_BAR; PG8_SCHED;
;             PG8_LDB(B1, 0, 1); PG8_STAGE(PG8_SB(0, 0), b2, voffB);
;             PG8_BAR; PG8_WAIT_L(0); PG8_MMA(0, 1, At, B1); PG8_BAR;
;             PG8_LDA(At, 0, 1); PG8_STAGE(PG8_SA(0, 0), a2, voffA);
;             PG8_BAR; PG8_WAIT_L(0); PG8_MMA(1, 0, At, B0); PG8_BAR; PG8_SCHED;
;             PG8_STAGE(PG8_SB(0, 1), b2 + hstepB, voffB);
;             PG8_WAIT_V(6); PG8_BAR; PG8_MMA(1, 1, At, B1); PG8_BAR;
.LBB0_1898:
	ds_read_b128 v[20:23], v180
	ds_read_b128 v[28:31], v180 offset:1024
	ds_read_b128 v[174:177], v180 offset:2048
	ds_read_b128 v[184:187], v180 offset:3072
	s_add_i32 s58, s26, 2
	s_add_u32 s27, s24, 0x4000
	s_addc_u32 s28, s25, 0
	s_cmp_eq_u32 s17, s26
	s_cselect_b32 s30, s20, s27
	s_cselect_b32 s31, s21, s28
	s_cselect_b32 s26, s22, s56
	s_cselect_b32 s27, s23, s57
	s_add_u32 s28, s30, 0x8000
	s_addc_u32 s29, s31, 0
	s_add_i32 m0, s34, 0xc000
	ds_read_b128 v[188:191], v181
	ds_read_b128 v[192:195], v181 offset:1024
	ds_read_b128 v[196:199], v181 offset:2048
	ds_read_b128 v[200:203], v181 offset:3072
	ds_read_b128 v[204:207], v181 offset:4096
	ds_read_b128 v[208:211], v181 offset:5120
	ds_read_b128 v[212:215], v181 offset:6144
	ds_read_b128 v[216:219], v181 offset:7168
	global_load_lds_dwordx4 v168, s[24:25]
	s_add_i32 m0, s34, 0xe000
	s_nop 0
	global_load_lds_dwordx4 v170, s[24:25]
	s_waitcnt lgkmcnt(8)
	s_barrier
	s_waitcnt lgkmcnt(0)
	s_setprio 1
	s_waitcnt lgkmcnt(0)
	v_mfma_f32_16x16x32_bf16 v[0:3], v[20:23], v[188:191], v[0:3]
	v_mfma_f32_16x16x32_bf16 v[4:7], v[174:177], v[188:191], v[4:7]
	v_mfma_f32_16x16x32_bf16 v[44:47], v[20:23], v[196:199], v[44:47]
	v_mfma_f32_16x16x32_bf16 v[36:39], v[174:177], v[196:199], v[36:39]
	v_mfma_f32_16x16x32_bf16 v[52:55], v[20:23], v[204:207], v[52:55]
	v_mfma_f32_16x16x32_bf16 v[48:51], v[174:177], v[204:207], v[48:51]
	v_mfma_f32_16x16x32_bf16 v[92:95], v[20:23], v[212:215], v[92:95]
	v_mfma_f32_16x16x32_bf16 v[84:87], v[174:177], v[212:215], v[84:87]
	v_mfma_f32_16x16x32_bf16 v[0:3], v[28:31], v[192:195], v[0:3]
	v_mfma_f32_16x16x32_bf16 v[4:7], v[184:187], v[192:195], v[4:7]
	v_mfma_f32_16x16x32_bf16 v[44:47], v[28:31], v[200:203], v[44:47]
	v_mfma_f32_16x16x32_bf16 v[36:39], v[184:187], v[200:203], v[36:39]
	v_mfma_f32_16x16x32_bf16 v[52:55], v[28:31], v[208:211], v[52:55]
	v_mfma_f32_16x16x32_bf16 v[48:51], v[184:187], v[208:211], v[48:51]
	v_mfma_f32_16x16x32_bf16 v[92:95], v[28:31], v[216:219], v[92:95]
	v_mfma_f32_16x16x32_bf16 v[84:87], v[184:187], v[216:219], v[84:87]
	s_setprio 0
	s_barrier
	s_add_i32 s59, s44, s33
	s_add_u32 s98, s26, s4
	s_addc_u32 s99, s27, s5
	s_mov_b32 m0, s59
	ds_read_b128 v[220:223], v182
	ds_read_b128 v[224:227], v182 offset:1024
	ds_read_b128 v[228:231], v182 offset:2048
	ds_read_b128 v[232:235], v182 offset:3072
	global_load_lds_dwordx4 v138, s[26:27]
	s_add_i32 m0, s59, 0x2000
	s_nop 0
	global_load_lds_dwordx4 v142, s[26:27]
	s_barrier
	s_waitcnt lgkmcnt(0)
	s_setprio 1
	s_waitcnt lgkmcnt(0)
	v_mfma_f32_16x16x32_bf16 v[12:15], v[220:223], v[188:191], v[12:15]
	v_mfma_f32_16x16x32_bf16 v[8:11], v[228:231], v[188:191], v[8:11]
	v_mfma_f32_16x16x32_bf16 v[24:27], v[220:223], v[196:199], v[24:27]
	v_mfma_f32_16x16x32_bf16 v[16:19], v[228:231], v[196:199], v[16:19]
	v_mfma_f32_16x16x32_bf16 v[40:43], v[220:223], v[204:207], v[40:43]
	v_mfma_f32_16x16x32_bf16 v[32:35], v[228:231], v[204:207], v[32:35]
	v_mfma_f32_16x16x32_bf16 v[56:59], v[220:223], v[212:215], v[56:59]
	v_mfma_f32_16x16x32_bf16 v[60:63], v[228:231], v[212:215], v[60:63]
	v_mfma_f32_16x16x32_bf16 v[12:15], v[224:227], v[192:195], v[12:15]
	v_mfma_f32_16x16x32_bf16 v[8:11], v[232:235], v[192:195], v[8:11]
	v_mfma_f32_16x16x32_bf16 v[24:27], v[224:227], v[200:203], v[24:27]
	v_mfma_f32_16x16x32_bf16 v[16:19], v[232:235], v[200:203], v[16:19]
	v_mfma_f32_16x16x32_bf16 v[40:43], v[224:227], v[208:211], v[40:43]
	v_mfma_f32_16x16x32_bf16 v[32:35], v[232:235], v[208:211], v[32:35]
	v_mfma_f32_16x16x32_bf16 v[56:59], v[224:227], v[216:219], v[56:59]
	v_mfma_f32_16x16x32_bf16 v[60:63], v[232:235], v[216:219], v[60:63]
	s_setprio 0
	s_barrier
	s_mov_b32 m0, s34
	ds_read_b128 v[188:191], v181 offset:16384
	ds_read_b128 v[192:195], v181 offset:17408
	ds_read_b128 v[196:199], v181 offset:18432
	ds_read_b128 v[200:203], v181 offset:19456
	ds_read_b128 v[204:207], v181 offset:20480
	ds_read_b128 v[208:211], v181 offset:21504
	ds_read_b128 v[212:215], v181 offset:22528
	ds_read_b128 v[216:219], v181 offset:23552
	global_load_lds_dwordx4 v136, s[30:31]
	s_mov_b32 m0, s35
	s_nop 0
	global_load_lds_dwordx4 v140, s[30:31]
	s_barrier
	s_waitcnt lgkmcnt(0)
	s_setprio 1
	s_waitcnt lgkmcnt(0)
	v_mfma_f32_16x16x32_bf16 v[64:67], v[20:23], v[188:191], v[64:67]
	v_mfma_f32_16x16x32_bf16 v[68:71], v[174:177], v[188:191], v[68:71]
	v_mfma_f32_16x16x32_bf16 v[108:111], v[20:23], v[196:199], v[108:111]
	v_mfma_f32_16x16x32_bf16 v[100:103], v[174:177], v[196:199], v[100:103]
	v_mfma_f32_16x16x32_bf16 v[116:119], v[20:23], v[204:207], v[116:119]
	v_mfma_f32_16x16x32_bf16 v[112:115], v[174:177], v[204:207], v[112:115]
	v_mfma_f32_16x16x32_bf16 v[20:23], v[20:23], v[212:215], v[132:135]
	v_mfma_f32_16x16x32_bf16 v[64:67], v[28:31], v[192:195], v[64:67]
	v_mfma_f32_16x16x32_bf16 v[68:71], v[184:187], v[192:195], v[68:71]
	v_mfma_f32_16x16x32_bf16 v[108:111], v[28:31], v[200:203], v[108:111]
	v_mfma_f32_16x16x32_bf16 v[100:103], v[184:187], v[200:203], v[100:103]
	v_mfma_f32_16x16x32_bf16 v[116:119], v[28:31], v[208:211], v[116:119]
	v_mfma_f32_16x16x32_bf16 v[112:115], v[184:187], v[208:211], v[112:115]
	v_mfma_f32_16x16x32_bf16 v[20:23], v[28:31], v[216:219], v[20:23]
	v_mfma_f32_16x16x32_bf16 v[28:31], v[174:177], v[212:215], v[128:131]
	v_mfma_f32_16x16x32_bf16 v[28:31], v[184:187], v[216:219], v[28:31]
	s_setprio 0
	s_barrier
	s_add_u32 s60, s26, 0x158000
	s_addc_u32 s61, s27, 0
	s_add_i32 s59, s45, s33
	s_mov_b32 m0, s59
	s_nop 0
	global_load_lds_dwordx4 v138, s[60:61]
	s_add_i32 m0, s59, 0x2000
	s_nop 0
	global_load_lds_dwordx4 v142, s[60:61]
	s_waitcnt vmcnt(6)
	s_barrier
; #define PG8_STAGE(bufoff, gbase, voff) do { _Pragma("unroll") for (int _i = 0; _i < 2; ++_i) \
;         __builtin_amdgcn_global_load_lds((const unsigned*)((const char*)(gbase) + (voff)[_i]), (LAS unsigned*)(lds + (bufoff) + ldsw + _i * 8192), 16, 0, 0); } while (0)
; #define PG8_LDA(dst, b, h) do { _Pragma("unroll") for (int m = 0; m < 4; ++m) _Pragma("unroll") for (int k = 0; k < 2; ++k) dst[m][k] = *(const LAS bf16x8*)(lds + PG8_SA(b, h) + aoff + m * 2048 + k * 1024); } while (0)
; #define PG8_LDB(dst, b, h) do { _Pragma("unroll") for (int n = 0; n < 2; ++n) _Pragma("unroll") for (int k = 0; k < 2; ++k) dst[n][k] = *(const LAS bf16x8*)(lds + PG8_SB(b, h) + boff + n * 2048 + k * 1024); } while (0)
; #define PG8_MMA(ai, bj, At, Bt) do { __builtin_amdgcn_s_setprio(1); _Pragma("unroll") for (int m = 0; m < 4; ++m) _Pragma("unroll") for (int n = 0; n < 2; ++n) _Pragma("unroll") for (int k = 0; k < 2; ++k) \
;         acc[ai][bj][m][n] = __builtin_amdgcn_mfma_f32_16x16x32_bf16(Bt[n][k], At[m][k], acc[ai][bj][m][n], 0, 0, 0); __builtin_amdgcn_s_setprio(0); } while (0)
; #define PG8_WAIT_V(n) asm volatile("s_waitcnt vmcnt(" #n ")" ::: "memory")
; #define PG8_WAIT_L(n) asm volatile("s_waitcnt lgkmcnt(" #n ")" ::: "memory")
; #define PG8_BAR __builtin_amdgcn_s_barrier()
; #define PG8_SCHED __builtin_amdgcn_sched_barrier(0)
; template <class Epi, class Sched, bool ATILE = false>
; __device__ __forceinline__ void gemm_phase(LAS unsigned char* lds, const Gemm g, const Sched& S, const Epi& E) {
;     ...
;             PG8_WAIT_V(6); PG8_BAR; PG8_MMA(1, 1, At, B1); PG8_BAR;
;             PG8_LDB(B0, 1, 0); PG8_SCHED; PG8_LDA(At, 1, 0); PG8_STAGE(PG8_SA(0, 1), a2 + hstepA, voffA);
;             PG8_WAIT_L(8); PG8_BAR; PG8_WAIT_L(0); PG8_MMA(0, 0, At, B0); PG8_BAR; PG8_SCHED;
;             PG8_LDB(B1, 1, 1); PG8_STAGE(PG8_SB(1, 0), b3, voffB);
;             PG8_BAR; PG8_WAIT_L(0); PG8_MMA(0, 1, At, B1); PG8_BAR;
;             PG8_LDA(At, 1, 1); PG8_STAGE(PG8_SA(1, 0), a3, voffA);
	s_setprio 1
	v_mfma_f32_16x16x32_bf16 v[76:79], v[220:223], v[188:191], v[76:79]
	v_mfma_f32_16x16x32_bf16 v[72:75], v[228:231], v[188:191], v[72:75]
	v_mfma_f32_16x16x32_bf16 v[88:91], v[220:223], v[196:199], v[88:91]
	v_mfma_f32_16x16x32_bf16 v[80:83], v[228:231], v[196:199], v[80:83]
	v_mfma_f32_16x16x32_bf16 v[104:107], v[220:223], v[204:207], v[104:107]
	v_mfma_f32_16x16x32_bf16 v[96:99], v[228:231], v[204:207], v[96:99]
	v_mfma_f32_16x16x32_bf16 v[120:123], v[220:223], v[212:215], v[120:123]
	v_mfma_f32_16x16x32_bf16 v[124:127], v[228:231], v[212:215], v[124:127]
	v_mfma_f32_16x16x32_bf16 v[76:79], v[224:227], v[192:195], v[76:79]
	v_mfma_f32_16x16x32_bf16 v[72:75], v[232:235], v[192:195], v[72:75]
	v_mfma_f32_16x16x32_bf16 v[88:91], v[224:227], v[200:203], v[88:91]
	v_mfma_f32_16x16x32_bf16 v[80:83], v[232:235], v[200:203], v[80:83]
	v_mfma_f32_16x16x32_bf16 v[104:107], v[224:227], v[208:211], v[104:107]
	v_mfma_f32_16x16x32_bf16 v[96:99], v[232:235], v[208:211], v[96:99]
	v_mfma_f32_16x16x32_bf16 v[120:123], v[224:227], v[216:219], v[120:123]
	v_mfma_f32_16x16x32_bf16 v[124:127], v[232:235], v[216:219], v[124:127]
	s_setprio 0
	s_barrier
	s_add_i32 s59, 0, 0x18000
	v_add_u32_e32 v183, s59, v157
	ds_read_b128 v[128:131], v183
	ds_read_b128 v[132:135], v183 offset:1024
	ds_read_b128 v[174:177], v183 offset:2048
	ds_read_b128 v[184:187], v183 offset:3072
	s_add_u32 s30, s30, 0x4000
	s_addc_u32 s31, s31, 0
	s_mov_b32 m0, s36
	ds_read_b128 v[188:191], v181 offset:32768
	ds_read_b128 v[192:195], v181 offset:33792
	ds_read_b128 v[196:199], v181 offset:34816
	ds_read_b128 v[200:203], v181 offset:35840
	ds_read_b128 v[204:207], v181 offset:36864
	ds_read_b128 v[208:211], v181 offset:37888
	ds_read_b128 v[212:215], v181 offset:38912
	ds_read_b128 v[216:219], v181 offset:39936
	global_load_lds_dwordx4 v136, s[30:31]
	s_mov_b32 m0, s37
	s_nop 0
	global_load_lds_dwordx4 v140, s[30:31]
	s_waitcnt lgkmcnt(8)
	s_barrier
	s_waitcnt lgkmcnt(0)
	s_setprio 1
	s_waitcnt lgkmcnt(0)
	v_mfma_f32_16x16x32_bf16 v[0:3], v[128:131], v[188:191], v[0:3]
	v_mfma_f32_16x16x32_bf16 v[4:7], v[174:177], v[188:191], v[4:7]
	v_mfma_f32_16x16x32_bf16 v[44:47], v[128:131], v[196:199], v[44:47]
	v_mfma_f32_16x16x32_bf16 v[36:39], v[174:177], v[196:199], v[36:39]
	v_mfma_f32_16x16x32_bf16 v[52:55], v[128:131], v[204:207], v[52:55]
	v_mfma_f32_16x16x32_bf16 v[48:51], v[174:177], v[204:207], v[48:51]
	v_mfma_f32_16x16x32_bf16 v[92:95], v[128:131], v[212:215], v[92:95]
	v_mfma_f32_16x16x32_bf16 v[84:87], v[174:177], v[212:215], v[84:87]
	v_mfma_f32_16x16x32_bf16 v[0:3], v[132:135], v[192:195], v[0:3]
	v_mfma_f32_16x16x32_bf16 v[4:7], v[184:187], v[192:195], v[4:7]
	v_mfma_f32_16x16x32_bf16 v[44:47], v[132:135], v[200:203], v[44:47]
	v_mfma_f32_16x16x32_bf16 v[36:39], v[184:187], v[200:203], v[36:39]
	v_mfma_f32_16x16x32_bf16 v[52:55], v[132:135], v[208:211], v[52:55]
	v_mfma_f32_16x16x32_bf16 v[48:51], v[184:187], v[208:211], v[48:51]
	v_mfma_f32_16x16x32_bf16 v[92:95], v[132:135], v[216:219], v[92:95]
	v_mfma_f32_16x16x32_bf16 v[84:87], v[184:187], v[216:219], v[84:87]
	s_setprio 0
	s_barrier
	s_add_i32 s30, 0, 0x1c000
	s_add_i32 s31, s59, s33
	v_add_u32_e32 v183, s30, v157
	s_mov_b32 m0, s31
	ds_read_b128 v[220:223], v183
	ds_read_b128 v[224:227], v183 offset:1024
	ds_read_b128 v[228:231], v183 offset:2048
	ds_read_b128 v[232:235], v183 offset:3072
	global_load_lds_dwordx4 v138, s[98:99]
	s_add_i32 m0, s31, 0x2000
	s_nop 0
	global_load_lds_dwordx4 v142, s[98:99]
	s_barrier
	s_waitcnt lgkmcnt(0)
	s_setprio 1
	s_waitcnt lgkmcnt(0)
	v_mfma_f32_16x16x32_bf16 v[12:15], v[220:223], v[188:191], v[12:15]
	v_mfma_f32_16x16x32_bf16 v[8:11], v[228:231], v[188:191], v[8:11]
	v_mfma_f32_16x16x32_bf16 v[24:27], v[220:223], v[196:199], v[24:27]
	v_mfma_f32_16x16x32_bf16 v[16:19], v[228:231], v[196:199], v[16:19]
	v_mfma_f32_16x16x32_bf16 v[40:43], v[220:223], v[204:207], v[40:43]
	v_mfma_f32_16x16x32_bf16 v[32:35], v[228:231], v[204:207], v[32:35]
	v_mfma_f32_16x16x32_bf16 v[56:59], v[220:223], v[212:215], v[56:59]
	v_mfma_f32_16x16x32_bf16 v[60:63], v[228:231], v[212:215], v[60:63]
	v_mfma_f32_16x16x32_bf16 v[12:15], v[224:227], v[192:195], v[12:15]
	v_mfma_f32_16x16x32_bf16 v[8:11], v[232:235], v[192:195], v[8:11]
	v_mfma_f32_16x16x32_bf16 v[24:27], v[224:227], v[200:203], v[24:27]
	v_mfma_f32_16x16x32_bf16 v[16:19], v[232:235], v[200:203], v[16:19]
	v_mfma_f32_16x16x32_bf16 v[40:43], v[224:227], v[208:211], v[40:43]
	v_mfma_f32_16x16x32_bf16 v[32:35], v[232:235], v[208:211], v[32:35]
	v_mfma_f32_16x16x32_bf16 v[56:59], v[224:227], v[216:219], v[56:59]
	v_mfma_f32_16x16x32_bf16 v[60:63], v[232:235], v[216:219], v[60:63]
	s_setprio 0
	s_barrier
	s_mov_b32 m0, s39
	ds_read_b128 v[188:191], v181 offset:49152
	ds_read_b128 v[192:195], v181 offset:50176
	ds_read_b128 v[196:199], v181 offset:51200
	ds_read_b128 v[200:203], v181 offset:52224
	ds_read_b128 v[204:207], v181 offset:53248
	ds_read_b128 v[208:211], v181 offset:54272
	ds_read_b128 v[212:215], v181 offset:55296
	ds_read_b128 v[216:219], v181 offset:56320
	global_load_lds_dwordx4 v136, s[28:29]
	s_mov_b32 m0, s40
	s_nop 0
	global_load_lds_dwordx4 v140, s[28:29]
	s_barrier
; __device__ __forceinline__ float bflo(unsigned w) { return __uint_as_float(w << 16); }
; __device__ __forceinline__ float bfhi(unsigned w) { return __uint_as_float(w & 0xffff0000u); }
; #define PG8_STAGE(bufoff, gbase, voff) do { _Pragma("unroll") for (int _i = 0; _i < 2; ++_i) \
;         __builtin_amdgcn_global_load_lds((const unsigned*)((const char*)(gbase) + (voff)[_i]), (LAS unsigned*)(lds + (bufoff) + ldsw + _i * 8192), 16, 0, 0); } while (0)
; #define PG8_LDA(dst, b, h) do { _Pragma("unroll") for (int m = 0; m < 4; ++m) _Pragma("unroll") for (int k = 0; k < 2; ++k) dst[m][k] = *(const LAS bf16x8*)(lds + PG8_SA(b, h) + aoff + m * 2048 + k * 1024); } while (0)
; #define PG8_MMA(ai, bj, At, Bt) do { __builtin_amdgcn_s_setprio(1); _Pragma("unroll") for (int m = 0; m < 4; ++m) _Pragma("unroll") for (int n = 0; n < 2; ++n) _Pragma("unroll") for (int k = 0; k < 2; ++k) \
;         acc[ai][bj][m][n] = __builtin_amdgcn_mfma_f32_16x16x32_bf16(Bt[n][k], At[m][k], acc[ai][bj][m][n], 0, 0, 0); __builtin_amdgcn_s_setprio(0); } while (0)
; #define PG8_WAIT_V(n) asm volatile("s_waitcnt vmcnt(" #n ")" ::: "memory")
; #define PG8_WAIT_L(n) asm volatile("s_waitcnt lgkmcnt(" #n ")" ::: "memory")
; #define PG8_BAR __builtin_amdgcn_s_barrier()
; #define PG8_SCHED __builtin_amdgcn_sched_barrier(0)
; template <class Epi, class Sched, bool ATILE = false>
; __device__ __forceinline__ void gemm_phase(LAS unsigned char* lds, const Gemm g, const Sched& S, const Epi& E) {
;     ...
;             PG8_BAR; PG8_WAIT_L(0); PG8_MMA(0, 1, At, B1); PG8_BAR;
;             PG8_LDA(At, 1, 1); PG8_STAGE(PG8_SA(1, 0), a3, voffA);
;             PG8_BAR; PG8_WAIT_L(0); PG8_MMA(1, 0, At, B0); PG8_BAR; PG8_SCHED;
;             PG8_STAGE(PG8_SB(1, 1), b3 + hstepB, voffB);
;             PG8_WAIT_V(6); PG8_BAR; PG8_MMA(1, 1, At, B1); PG8_BAR;
;     __device__ __forceinline__ void operator()(const f32x4 (&acc)[2][2][4][2], const Unit& u, int wr, int wc, int fr, int fq) const {
;     ...
;                     const f32x4 v0 = (f32x4){bflo(x.x), bfhi(x.x), bflo(x.y), bfhi(x.y)} + alpha * acc[ai][bj][m][0];
;                     const f32x4 v1 = (f32x4){bflo(x.z), bfhi(x.z), bflo(x.w), bfhi(x.w)} + alpha * acc[ai][bj][m][1];
	s_waitcnt lgkmcnt(0)
	s_setprio 1
	s_waitcnt lgkmcnt(0)
	v_mfma_f32_16x16x32_bf16 v[64:67], v[128:131], v[188:191], v[64:67]
	v_mfma_f32_16x16x32_bf16 v[108:111], v[128:131], v[196:199], v[108:111]
	v_mfma_f32_16x16x32_bf16 v[116:119], v[128:131], v[204:207], v[116:119]
	v_mfma_f32_16x16x32_bf16 v[20:23], v[128:131], v[212:215], v[20:23]
	v_mfma_f32_16x16x32_bf16 v[64:67], v[132:135], v[192:195], v[64:67]
	v_mfma_f32_16x16x32_bf16 v[68:71], v[174:177], v[188:191], v[68:71]
	v_mfma_f32_16x16x32_bf16 v[108:111], v[132:135], v[200:203], v[108:111]
	v_mfma_f32_16x16x32_bf16 v[100:103], v[174:177], v[196:199], v[100:103]
	v_mfma_f32_16x16x32_bf16 v[116:119], v[132:135], v[208:211], v[116:119]
	v_mfma_f32_16x16x32_bf16 v[112:115], v[174:177], v[204:207], v[112:115]
	v_mfma_f32_16x16x32_bf16 v[132:135], v[132:135], v[216:219], v[20:23]
	v_mfma_f32_16x16x32_bf16 v[20:23], v[174:177], v[212:215], v[28:31]
	v_mfma_f32_16x16x32_bf16 v[68:71], v[184:187], v[192:195], v[68:71]
	v_mfma_f32_16x16x32_bf16 v[100:103], v[184:187], v[200:203], v[100:103]
	v_mfma_f32_16x16x32_bf16 v[112:115], v[184:187], v[208:211], v[112:115]
	v_mfma_f32_16x16x32_bf16 v[128:131], v[184:187], v[216:219], v[20:23]
	s_setprio 0
	s_barrier
	s_add_u32 s26, s26, 0x158080
	s_addc_u32 s27, s27, 0
	s_add_i32 s28, s30, s33
	s_mov_b32 m0, s28
	s_nop 0
	global_load_lds_dwordx4 v138, s[26:27]
	s_add_i32 m0, s28, 0x2000
	s_nop 0
	global_load_lds_dwordx4 v142, s[26:27]
	s_waitcnt vmcnt(6)
	s_barrier
	s_setprio 1
	v_mfma_f32_16x16x32_bf16 v[20:23], v[220:223], v[188:191], v[76:79]
	v_mfma_f32_16x16x32_bf16 v[76:79], v[224:227], v[192:195], v[20:23]
	v_mfma_f32_16x16x32_bf16 v[20:23], v[228:231], v[188:191], v[72:75]
	v_mfma_f32_16x16x32_bf16 v[72:75], v[232:235], v[192:195], v[20:23]
	v_mfma_f32_16x16x32_bf16 v[20:23], v[220:223], v[196:199], v[88:91]
	v_mfma_f32_16x16x32_bf16 v[88:91], v[224:227], v[200:203], v[20:23]
	v_mfma_f32_16x16x32_bf16 v[20:23], v[228:231], v[196:199], v[80:83]
	v_mfma_f32_16x16x32_bf16 v[80:83], v[232:235], v[200:203], v[20:23]
	v_mfma_f32_16x16x32_bf16 v[20:23], v[220:223], v[204:207], v[104:107]
	v_mfma_f32_16x16x32_bf16 v[104:107], v[224:227], v[208:211], v[20:23]
	v_mfma_f32_16x16x32_bf16 v[20:23], v[228:231], v[204:207], v[96:99]
	v_mfma_f32_16x16x32_bf16 v[96:99], v[232:235], v[208:211], v[20:23]
	v_mfma_f32_16x16x32_bf16 v[20:23], v[220:223], v[212:215], v[120:123]
	v_mfma_f32_16x16x32_bf16 v[120:123], v[224:227], v[216:219], v[20:23]
	v_mfma_f32_16x16x32_bf16 v[20:23], v[228:231], v[212:215], v[124:127]
	v_mfma_f32_16x16x32_bf16 v[124:127], v[232:235], v[216:219], v[20:23]
	s_setprio 0
	s_barrier
	s_add_u32 s56, s56, 0x100
	s_addc_u32 s57, s57, 0
	s_add_u32 s24, s24, 0x10000
	s_addc_u32 s25, s25, 0
	s_cmp_ge_i32 s58, s55
	s_mov_b32 s26, s58
	s_cbranch_scc0 .LBB0_1898
	v_pk_mul_f32 v[2:3], v[2:3], 0.5 op_sel_hi:[1,0]
	v_pk_mul_f32 v[0:1], v[0:1], 0.5 op_sel_hi:[1,0]
	v_pk_mul_f32 v[6:7], v[6:7], 0.5 op_sel_hi:[1,0]
	v_pk_mul_f32 v[4:5], v[4:5], 0.5 op_sel_hi:[1,0]
	v_pk_mul_f32 v[22:23], v[14:15], 0.5 op_sel_hi:[1,0]
	v_pk_mul_f32 v[20:21], v[12:13], 0.5 op_sel_hi:[1,0]
	v_pk_mul_f32 v[30:31], v[10:11], 0.5 op_sel_hi:[1,0]
	v_pk_mul_f32 v[28:29], v[8:9], 0.5 op_sel_hi:[1,0]
	v_pk_mul_f32 v[10:11], v[46:47], 0.5 op_sel_hi:[1,0]
	v_pk_mul_f32 v[8:9], v[44:45], 0.5 op_sel_hi:[1,0]
	v_pk_mul_f32 v[14:15], v[38:39], 0.5 op_sel_hi:[1,0]
	v_pk_mul_f32 v[12:13], v[36:37], 0.5 op_sel_hi:[1,0]
	v_pk_mul_f32 v[38:39], v[26:27], 0.5 op_sel_hi:[1,0]
	v_pk_mul_f32 v[36:37], v[24:25], 0.5 op_sel_hi:[1,0]
	v_pk_mul_f32 v[46:47], v[18:19], 0.5 op_sel_hi:[1,0]
	v_pk_mul_f32 v[44:45], v[16:17], 0.5 op_sel_hi:[1,0]
	v_pk_mul_f32 v[18:19], v[54:55], 0.5 op_sel_hi:[1,0]
	v_pk_mul_f32 v[16:17], v[52:53], 0.5 op_sel_hi:[1,0]
	v_pk_mul_f32 v[26:27], v[50:51], 0.5 op_sel_hi:[1,0]
	v_pk_mul_f32 v[24:25], v[48:49], 0.5 op_sel_hi:[1,0]
	v_pk_mul_f32 v[50:51], v[42:43], 0.5 op_sel_hi:[1,0]
	v_pk_mul_f32 v[48:49], v[40:41], 0.5 op_sel_hi:[1,0]
	v_pk_mul_f32 v[54:55], v[34:35], 0.5 op_sel_hi:[1,0]
	v_pk_mul_f32 v[52:53], v[32:33], 0.5 op_sel_hi:[1,0]
	v_pk_mul_f32 v[34:35], v[94:95], 0.5 op_sel_hi:[1,0]
	v_pk_mul_f32 v[32:33], v[92:93], 0.5 op_sel_hi:[1,0]
	v_pk_mul_f32 v[42:43], v[86:87], 0.5 op_sel_hi:[1,0]
	v_pk_mul_f32 v[40:41], v[84:85], 0.5 op_sel_hi:[1,0]
	v_pk_mul_f32 v[58:59], v[58:59], 0.5 op_sel_hi:[1,0]
	v_pk_mul_f32 v[56:57], v[56:57], 0.5 op_sel_hi:[1,0]
	v_pk_mul_f32 v[62:63], v[62:63], 0.5 op_sel_hi:[1,0]
	v_pk_mul_f32 v[60:61], v[60:61], 0.5 op_sel_hi:[1,0]
	v_pk_mul_f32 v[66:67], v[66:67], 0.5 op_sel_hi:[1,0]
	v_pk_mul_f32 v[64:65], v[64:65], 0.5 op_sel_hi:[1,0]
	v_pk_mul_f32 v[70:71], v[70:71], 0.5 op_sel_hi:[1,0]
	v_pk_mul_f32 v[68:69], v[68:69], 0.5 op_sel_hi:[1,0]
	v_pk_mul_f32 v[86:87], v[78:79], 0.5 op_sel_hi:[1,0]
	v_pk_mul_f32 v[84:85], v[76:77], 0.5 op_sel_hi:[1,0]
	v_pk_mul_f32 v[94:95], v[74:75], 0.5 op_sel_hi:[1,0]
	v_pk_mul_f32 v[92:93], v[72:73], 0.5 op_sel_hi:[1,0]
	v_pk_mul_f32 v[74:75], v[110:111], 0.5 op_sel_hi:[1,0]
	v_pk_mul_f32 v[72:73], v[108:109], 0.5 op_sel_hi:[1,0]
	v_pk_mul_f32 v[78:79], v[102:103], 0.5 op_sel_hi:[1,0]
	v_pk_mul_f32 v[76:77], v[100:101], 0.5 op_sel_hi:[1,0]
	v_pk_mul_f32 v[102:103], v[90:91], 0.5 op_sel_hi:[1,0]
	v_pk_mul_f32 v[100:101], v[88:89], 0.5 op_sel_hi:[1,0]
	v_pk_mul_f32 v[110:111], v[82:83], 0.5 op_sel_hi:[1,0]
	v_pk_mul_f32 v[108:109], v[80:81], 0.5 op_sel_hi:[1,0]
	v_pk_mul_f32 v[82:83], v[118:119], 0.5 op_sel_hi:[1,0]
	v_pk_mul_f32 v[80:81], v[116:117], 0.5 op_sel_hi:[1,0]
	v_pk_mul_f32 v[90:91], v[114:115], 0.5 op_sel_hi:[1,0]
	v_pk_mul_f32 v[88:89], v[112:113], 0.5 op_sel_hi:[1,0]
	v_pk_mul_f32 v[114:115], v[106:107], 0.5 op_sel_hi:[1,0]
	v_pk_mul_f32 v[112:113], v[104:105], 0.5 op_sel_hi:[1,0]
	v_pk_mul_f32 v[118:119], v[98:99], 0.5 op_sel_hi:[1,0]
	v_pk_mul_f32 v[116:117], v[96:97], 0.5 op_sel_hi:[1,0]
	v_pk_mul_f32 v[98:99], v[134:135], 0.5 op_sel_hi:[1,0]
	v_pk_mul_f32 v[96:97], v[132:133], 0.5 op_sel_hi:[1,0]
	v_pk_mul_f32 v[106:107], v[130:131], 0.5 op_sel_hi:[1,0]
	v_pk_mul_f32 v[104:105], v[128:129], 0.5 op_sel_hi:[1,0]
	v_pk_mul_f32 v[122:123], v[122:123], 0.5 op_sel_hi:[1,0]
	v_pk_mul_f32 v[120:121], v[120:121], 0.5 op_sel_hi:[1,0]
	v_pk_mul_f32 v[126:127], v[126:127], 0.5 op_sel_hi:[1,0]
	v_pk_mul_f32 v[124:125], v[124:125], 0.5 op_sel_hi:[1,0]
	s_branch .LBB0_1903
